# v7 + GEMM prologue drains moved ahead of the first staging load (U, gates, W_out), EpiUT row biases fetched up front, phase-0 matvec weight slab prefetched with the conditioning vectors
# baseline (speedup 1.0000x reference)
.LBB0_34:
	v_mov_b32_e32 v55, v234
	s_nop 0
	v_cmp_lt_i32_e32 vcc, s69, v55
	v_lshlrev_b32_e32 v4, 2, v55
	s_and_saveexec_b64 s[8:9], vcc
	s_xor_b64 s[8:9], exec, s[8:9]
	v_lshlrev_b32_e32 v4, 2, v55
	s_andn2_saveexec_b64 s[8:9], s[8:9]
	s_cbranch_execz .LBB0_45
	v_add_u32_e32 v5, 0, v4
	global_load_dword v84, v4, s[18:19]
	global_load_dword v85, v4, s[18:19] offset:2048
	global_load_dword v86, v4, s[16:17]
	global_load_dword v87, v4, s[16:17] offset:2048
	s_add_u32 s10, s16, 0x1000
	s_addc_u32 s11, s17, 0
	global_load_dword v88, v4, s[10:11]
	global_load_dword v89, v4, s[10:11] offset:2048
	s_add_u32 s10, s10, 0x1000
	s_addc_u32 s11, s11, 0
	global_load_dword v90, v4, s[10:11]
	global_load_dword v91, v4, s[10:11] offset:2048
	s_add_u32 s10, s10, 0x1000
	s_addc_u32 s11, s11, 0
	global_load_dword v92, v4, s[10:11]
	global_load_dword v93, v4, s[10:11] offset:2048
	s_add_u32 s10, s10, 0x1000
	s_addc_u32 s11, s11, 0
	global_load_dword v94, v4, s[10:11]
	global_load_dword v95, v4, s[10:11] offset:2048
	s_add_u32 s10, s10, 0x1000
	s_addc_u32 s11, s11, 0
	global_load_dword v96, v4, s[10:11]
	global_load_dword v97, v4, s[10:11] offset:2048
	s_add_u32 s10, s10, 0x1000
	s_addc_u32 s11, s11, 0
	global_load_dword v98, v4, s[10:11]
	global_load_dword v99, v4, s[10:11] offset:2048
	s_add_u32 s10, s10, 0x1000
	s_addc_u32 s11, s11, 0
	global_load_dword v100, v4, s[10:11]
	global_load_dword v101, v4, s[10:11] offset:2048
	s_lshl_b32 s98, s75, 7
	s_add_u32 s98, s20, s98
	s_addc_u32 s99, s21, 0
	v_lshrrev_b32_e32 v252, 3, v55
	v_and_b32_e32 v253, 7, v55
	v_mul_u32_u24_e32 v252, 0x6000, v252
	v_lshl_add_u32 v252, v253, 4, v252
	global_load_dwordx4 v[200:203], v252, s[98:99]
	s_add_u32 s100, s98, 0x180000
	s_addc_u32 s101, s99, 0
	global_load_dwordx4 v[204:207], v252, s[100:101]
	s_add_u32 s100, s98, 0x300000
	s_addc_u32 s101, s99, 0
	global_load_dwordx4 v[208:211], v252, s[100:101]
	s_add_u32 s100, s98, 0x480000
	s_addc_u32 s101, s99, 0
	global_load_dwordx4 v[212:215], v252, s[100:101]
	s_add_u32 s100, s98, 0x600000
	s_addc_u32 s101, s99, 0
	global_load_dwordx4 v[216:219], v252, s[100:101]
	s_add_u32 s100, s98, 0x780000
	s_addc_u32 s101, s99, 0
	global_load_dwordx4 v[220:223], v252, s[100:101]
	s_add_u32 s100, s98, 0x900000
	s_addc_u32 s101, s99, 0
	global_load_dwordx4 v[224:227], v252, s[100:101]
	s_add_u32 s100, s98, 0xa80000
	s_addc_u32 s101, s99, 0
	global_load_dwordx4 v[228:231], v252, s[100:101]
	s_add_u32 s100, s98, 0xc00000
	s_addc_u32 s101, s99, 0
	global_load_dwordx4 v[236:239], v252, s[100:101]
	s_add_u32 s100, s98, 0xd80000
	s_addc_u32 s101, s99, 0
	global_load_dwordx4 v[240:243], v252, s[100:101]
	s_add_u32 s100, s98, 0xf00000
	s_addc_u32 s101, s99, 0
	global_load_dwordx4 v[244:247], v252, s[100:101]
	s_add_u32 s100, s98, 0x1080000
	s_addc_u32 s101, s99, 0
	global_load_dwordx4 v[248:251], v252, s[100:101]
	s_waitcnt vmcnt(29)
	v_mul_f32_e32 v102, 0xbfb8aa3b, v84
	v_exp_f32_e32 v102, v102
	s_nop 0
	v_add_f32_e32 v102, 1.0, v102
	v_rcp_f32_e32 v102, v102
	s_nop 0
	v_mul_f32_e32 v84, v84, v102
	ds_write_b32 v5, v84 offset:0
	s_waitcnt vmcnt(28)
	v_mul_f32_e32 v102, 0xbfb8aa3b, v85
	v_exp_f32_e32 v102, v102
	s_nop 0
	v_add_f32_e32 v102, 1.0, v102
	v_rcp_f32_e32 v102, v102
	s_nop 0
	v_mul_f32_e32 v85, v85, v102
	ds_write_b32 v5, v85 offset:2048
	s_waitcnt vmcnt(27)
	v_mul_f32_e32 v102, 0xbfb8aa3b, v86
	v_exp_f32_e32 v102, v102
	s_nop 0
	v_add_f32_e32 v102, 1.0, v102
	v_rcp_f32_e32 v102, v102
	s_nop 0
	v_mul_f32_e32 v86, v86, v102
	ds_write_b32 v5, v86 offset:4096
	s_waitcnt vmcnt(26)
	v_mul_f32_e32 v102, 0xbfb8aa3b, v87
	v_exp_f32_e32 v102, v102
	s_nop 0
	v_add_f32_e32 v102, 1.0, v102
	v_rcp_f32_e32 v102, v102
	s_nop 0
	v_mul_f32_e32 v87, v87, v102
	ds_write_b32 v5, v87 offset:6144
	s_waitcnt vmcnt(25)
	v_mul_f32_e32 v102, 0xbfb8aa3b, v88
	v_exp_f32_e32 v102, v102
	s_nop 0
	v_add_f32_e32 v102, 1.0, v102
	v_rcp_f32_e32 v102, v102
	s_nop 0
	v_mul_f32_e32 v88, v88, v102
	ds_write_b32 v5, v88 offset:8192
	s_waitcnt vmcnt(24)
	v_mul_f32_e32 v102, 0xbfb8aa3b, v89
	v_exp_f32_e32 v102, v102
	s_nop 0
	v_add_f32_e32 v102, 1.0, v102
	v_rcp_f32_e32 v102, v102
	s_nop 0
	v_mul_f32_e32 v89, v89, v102
	ds_write_b32 v5, v89 offset:10240
	s_waitcnt vmcnt(23)
	v_mul_f32_e32 v102, 0xbfb8aa3b, v90
	v_exp_f32_e32 v102, v102
	s_nop 0
	v_add_f32_e32 v102, 1.0, v102
	v_rcp_f32_e32 v102, v102
	s_nop 0
	v_mul_f32_e32 v90, v90, v102
	ds_write_b32 v5, v90 offset:12288
	s_waitcnt vmcnt(22)
	v_mul_f32_e32 v102, 0xbfb8aa3b, v91
	v_exp_f32_e32 v102, v102
	s_nop 0
	v_add_f32_e32 v102, 1.0, v102
	v_rcp_f32_e32 v102, v102
	s_nop 0
	v_mul_f32_e32 v91, v91, v102
	ds_write_b32 v5, v91 offset:14336
	s_waitcnt vmcnt(21)
	v_mul_f32_e32 v102, 0xbfb8aa3b, v92
	v_exp_f32_e32 v102, v102
	s_nop 0
	v_add_f32_e32 v102, 1.0, v102
	v_rcp_f32_e32 v102, v102
	s_nop 0
	v_mul_f32_e32 v92, v92, v102
	ds_write_b32 v5, v92 offset:16384
	s_waitcnt vmcnt(20)
	v_mul_f32_e32 v102, 0xbfb8aa3b, v93
	v_exp_f32_e32 v102, v102
	s_nop 0
	v_add_f32_e32 v102, 1.0, v102
	v_rcp_f32_e32 v102, v102
	s_nop 0
	v_mul_f32_e32 v93, v93, v102
	ds_write_b32 v5, v93 offset:18432
	s_waitcnt vmcnt(19)
	v_mul_f32_e32 v102, 0xbfb8aa3b, v94
	v_exp_f32_e32 v102, v102
	s_nop 0
	v_add_f32_e32 v102, 1.0, v102
	v_rcp_f32_e32 v102, v102
	s_nop 0
	v_mul_f32_e32 v94, v94, v102
	ds_write_b32 v5, v94 offset:20480
	s_waitcnt vmcnt(18)
	v_mul_f32_e32 v102, 0xbfb8aa3b, v95
	v_exp_f32_e32 v102, v102
	s_nop 0
	v_add_f32_e32 v102, 1.0, v102
	v_rcp_f32_e32 v102, v102
	s_nop 0
	v_mul_f32_e32 v95, v95, v102
	ds_write_b32 v5, v95 offset:22528
	s_waitcnt vmcnt(17)
	v_mul_f32_e32 v102, 0xbfb8aa3b, v96
	v_exp_f32_e32 v102, v102
	s_nop 0
	v_add_f32_e32 v102, 1.0, v102
	v_rcp_f32_e32 v102, v102
	s_nop 0
	v_mul_f32_e32 v96, v96, v102
	ds_write_b32 v5, v96 offset:24576
	s_waitcnt vmcnt(16)
	v_mul_f32_e32 v102, 0xbfb8aa3b, v97
	v_exp_f32_e32 v102, v102
	s_nop 0
	v_add_f32_e32 v102, 1.0, v102
	v_rcp_f32_e32 v102, v102
	s_nop 0
	v_mul_f32_e32 v97, v97, v102
	ds_write_b32 v5, v97 offset:26624
	s_waitcnt vmcnt(15)
	v_mul_f32_e32 v102, 0xbfb8aa3b, v98
	v_exp_f32_e32 v102, v102
	s_nop 0
	v_add_f32_e32 v102, 1.0, v102
	v_rcp_f32_e32 v102, v102
	s_nop 0
	v_mul_f32_e32 v98, v98, v102
	ds_write_b32 v5, v98 offset:28672
	s_waitcnt vmcnt(14)
	v_mul_f32_e32 v102, 0xbfb8aa3b, v99
	v_exp_f32_e32 v102, v102
	s_nop 0
	v_add_f32_e32 v102, 1.0, v102
	v_rcp_f32_e32 v102, v102
	s_nop 0
	v_mul_f32_e32 v99, v99, v102
	ds_write_b32 v5, v99 offset:30720
	s_waitcnt vmcnt(13)
	v_mul_f32_e32 v102, 0xbfb8aa3b, v100
	v_exp_f32_e32 v102, v102
	s_nop 0
	v_add_f32_e32 v102, 1.0, v102
	v_rcp_f32_e32 v102, v102
	s_nop 0
	v_mul_f32_e32 v100, v100, v102
	ds_write_b32 v5, v100 offset:32768
	s_waitcnt vmcnt(12)
	v_mul_f32_e32 v102, 0xbfb8aa3b, v101
	v_exp_f32_e32 v102, v102
	s_nop 0
	v_add_f32_e32 v102, 1.0, v102
	v_rcp_f32_e32 v102, v102
	s_nop 0
	v_mul_f32_e32 v101, v101, v102
	ds_write_b32 v5, v101 offset:34816
	s_branch .LBB0_45

.LBB0_45:
	s_or_b64 exec, exec, s[8:9]
	s_lshl_b32 s8, s75, 5
	s_ashr_i32 s9, s8, 31
	s_lshl_b64 s[10:11], s[8:9], 2
	s_add_u32 s10, s20, s10
	v_and_b32_e32 v2, 28, v4
	s_addc_u32 s11, s21, s11
	v_lshlrev_b32_e32 v12, 2, v2
	v_ashrrev_i32_e32 v112, 3, v55
	v_lshl_add_u64 v[64:65], s[10:11], 0, v[12:13]
	v_mad_i64_i32 v[2:3], s[10:11], v112, s72, v[64:65]
	s_waitcnt lgkmcnt(0)
	s_barrier
	s_waitcnt vmcnt(0)
	v_mov_b64_e32 v[6:7], v[200:201]
	v_mov_b64_e32 v[8:9], v[202:203]
	s_add_u32 s100, s98, 0x1380000
	s_addc_u32 s101, s99, 0
	global_load_dwordx4 v[200:203], v252, s[100:101]
	v_add_u32_e32 v2, 64, v112
	v_mad_i64_i32 v[2:3], s[10:11], v2, s72, v[64:65]
	v_mov_b64_e32 v[2:3], v[204:205]
	v_mov_b64_e32 v[4:5], v[206:207]
	s_add_u32 s100, s98, 0x1200000
	s_addc_u32 s101, s99, 0
	global_load_dwordx4 v[204:207], v252, s[100:101]
	v_add_u32_e32 v72, 0x80, v112
	v_lshl_add_u32 v12, v112, 2, 0
	v_add_u32_e32 v76, 0xc0, v112
	v_mad_i64_i32 v[72:73], s[10:11], v72, s72, v[64:65]
	ds_read2st64_b32 v[80:81], v12 offset1:1
	ds_read2st64_b32 v[84:85], v12 offset0:2 offset1:3
	ds_read2st64_b32 v[86:87], v12 offset0:4 offset1:5
	ds_read2st64_b32 v[66:67], v12 offset0:6 offset1:7
	ds_read2st64_b32 v[82:83], v12 offset0:16 offset1:17
	ds_read2st64_b32 v[88:89], v12 offset0:18 offset1:19
	ds_read2st64_b32 v[90:91], v12 offset0:20 offset1:21
	ds_read2st64_b32 v[68:69], v12 offset0:22 offset1:23
	ds_read2st64_b32 v[92:93], v12 offset0:32 offset1:33
	ds_read2st64_b32 v[94:95], v12 offset0:34 offset1:35
	ds_read2st64_b32 v[96:97], v12 offset0:36 offset1:37
	ds_read2st64_b32 v[70:71], v12 offset0:38 offset1:39
	v_mov_b64_e32 v[72:73], v[208:209]
	v_mov_b64_e32 v[74:75], v[210:211]
	s_add_u32 s100, s98, 0x1500000
	s_addc_u32 s101, s99, 0
	global_load_dwordx4 v[208:211], v252, s[100:101]
	v_mad_i64_i32 v[76:77], s[10:11], v76, s72, v[64:65]
	ds_read2st64_b32 v[98:99], v12 offset0:48 offset1:49
	ds_read2st64_b32 v[100:101], v12 offset0:50 offset1:51
	ds_read2st64_b32 v[102:103], v12 offset0:52 offset1:53
	ds_read2st64_b32 v[106:107], v12 offset0:54 offset1:55
	ds_read2st64_b32 v[104:105], v12 offset0:64 offset1:65
	ds_read2st64_b32 v[108:109], v12 offset0:66 offset1:67
	ds_read2st64_b32 v[110:111], v12 offset0:68 offset1:69
	ds_read2st64_b32 v[118:119], v12 offset0:70 offset1:71
	ds_read2st64_b32 v[114:115], v12 offset0:80 offset1:81
	ds_read2st64_b32 v[116:117], v12 offset0:82 offset1:83
	ds_read2st64_b32 v[120:121], v12 offset0:84 offset1:85
	ds_read2st64_b32 v[122:123], v12 offset0:86 offset1:87
	ds_read2st64_b32 v[124:125], v12 offset0:96 offset1:97
	ds_read2st64_b32 v[126:127], v12 offset0:98 offset1:99
	ds_read2st64_b32 v[140:141], v12 offset0:100 offset1:101
	ds_read2st64_b32 v[142:143], v12 offset0:102 offset1:103
	v_mov_b64_e32 v[76:77], v[212:213]
	v_mov_b64_e32 v[78:79], v[214:215]
	s_add_u32 s100, s98, 0x1680000
	s_addc_u32 s101, s99, 0
	global_load_dwordx4 v[212:215], v252, s[100:101]
	ds_read2st64_b32 v[144:145], v12 offset0:112 offset1:113
	ds_read2st64_b32 v[146:147], v12 offset0:114 offset1:115
	ds_read2st64_b32 v[148:149], v12 offset0:116 offset1:117
	ds_read2st64_b32 v[150:151], v12 offset0:118 offset1:119
	ds_read2st64_b32 v[152:153], v12 offset0:128 offset1:129
	ds_read2st64_b32 v[154:155], v12 offset0:130 offset1:131
	ds_read2st64_b32 v[156:157], v12 offset0:132 offset1:133
	ds_read2st64_b32 v[158:159], v12 offset0:134 offset1:135
	v_add_u32_e32 v113, 0x100, v112
	s_waitcnt lgkmcnt(14)
	v_mov_b32_e32 v162, v81
	v_mov_b32_e32 v164, v83
	v_pk_fma_f32 v[166:167], v[8:9], v[80:81], 0 op_sel_hi:[1,0,0]
	v_pk_fma_f32 v[80:81], v[6:7], v[80:81], 0 op_sel_hi:[1,0,0]
	v_pk_fma_f32 v[168:169], v[8:9], v[82:83], 0 op_sel_hi:[1,0,0]
	v_pk_fma_f32 v[82:83], v[6:7], v[82:83], 0 op_sel_hi:[1,0,0]
	v_pk_fma_f32 v[172:173], v[6:7], v[92:93], 0 op_sel_hi:[1,0,0]
	v_pk_fma_f32 v[176:177], v[6:7], v[98:99], 0 op_sel_hi:[1,0,0]
	v_pk_fma_f32 v[180:181], v[6:7], v[104:105], 0 op_sel_hi:[1,0,0]
	v_pk_fma_f32 v[184:185], v[6:7], v[114:115], 0 op_sel_hi:[1,0,0]
	s_waitcnt lgkmcnt(11)
	v_pk_fma_f32 v[188:189], v[6:7], v[124:125], 0 op_sel_hi:[1,0,0]
	s_waitcnt lgkmcnt(7)
	v_pk_fma_f32 v[192:193], v[6:7], v[144:145], 0 op_sel_hi:[1,0,0]
	s_waitcnt lgkmcnt(3)
	v_pk_fma_f32 v[196:197], v[6:7], v[152:153], 0 op_sel_hi:[1,0,0]
	v_mad_i64_i32 v[6:7], s[10:11], v113, s72, v[64:65]
	v_pk_fma_f32 v[170:171], v[8:9], v[92:93], 0 op_sel_hi:[1,0,0]
	v_pk_fma_f32 v[174:175], v[8:9], v[98:99], 0 op_sel_hi:[1,0,0]
	v_pk_fma_f32 v[178:179], v[8:9], v[104:105], 0 op_sel_hi:[1,0,0]
	v_pk_fma_f32 v[182:183], v[8:9], v[114:115], 0 op_sel_hi:[1,0,0]
	v_pk_fma_f32 v[186:187], v[8:9], v[124:125], 0 op_sel_hi:[1,0,0]
	v_pk_fma_f32 v[190:191], v[8:9], v[144:145], 0 op_sel_hi:[1,0,0]
	v_pk_fma_f32 v[194:195], v[8:9], v[152:153], 0 op_sel_hi:[1,0,0]
	v_mov_b64_e32 v[6:7], v[216:217]
	v_mov_b64_e32 v[8:9], v[218:219]
	v_pk_fma_f32 v[166:167], v[4:5], v[162:163], v[166:167] op_sel_hi:[1,0,1]
	v_pk_fma_f32 v[162:163], v[2:3], v[162:163], v[80:81] op_sel_hi:[1,0,1]
	v_mov_b32_e32 v80, v93
	v_pk_fma_f32 v[92:93], v[4:5], v[80:81], v[170:171] op_sel_hi:[1,0,1]
	v_pk_fma_f32 v[170:171], v[2:3], v[80:81], v[172:173] op_sel_hi:[1,0,1]
	v_mov_b32_e32 v80, v99
	v_pk_fma_f32 v[98:99], v[4:5], v[80:81], v[174:175] op_sel_hi:[1,0,1]
	v_pk_fma_f32 v[172:173], v[2:3], v[80:81], v[176:177] op_sel_hi:[1,0,1]
	v_mov_b32_e32 v80, v105
	v_pk_fma_f32 v[104:105], v[4:5], v[80:81], v[178:179] op_sel_hi:[1,0,1]
	v_pk_fma_f32 v[174:175], v[2:3], v[80:81], v[180:181] op_sel_hi:[1,0,1]
	v_mov_b32_e32 v80, v115
	v_pk_fma_f32 v[114:115], v[4:5], v[80:81], v[182:183] op_sel_hi:[1,0,1]
	v_pk_fma_f32 v[176:177], v[2:3], v[80:81], v[184:185] op_sel_hi:[1,0,1]
	v_mov_b32_e32 v80, v125
	v_pk_fma_f32 v[124:125], v[4:5], v[80:81], v[186:187] op_sel_hi:[1,0,1]
	v_pk_fma_f32 v[178:179], v[2:3], v[80:81], v[188:189] op_sel_hi:[1,0,1]
	v_mov_b32_e32 v80, v145
	v_pk_fma_f32 v[144:145], v[4:5], v[80:81], v[190:191] op_sel_hi:[1,0,1]
	v_pk_fma_f32 v[180:181], v[2:3], v[80:81], v[192:193] op_sel_hi:[1,0,1]
	v_add_u32_e32 v80, 0x140, v112
	v_mad_i64_i32 v[80:81], s[10:11], v80, s72, v[64:65]
	v_pk_fma_f32 v[168:169], v[4:5], v[164:165], v[168:169] op_sel_hi:[1,0,1]
	v_pk_fma_f32 v[164:165], v[2:3], v[164:165], v[82:83] op_sel_hi:[1,0,1]
	v_mov_b64_e32 v[80:81], v[220:221]
	v_mov_b64_e32 v[82:83], v[222:223]
	v_mov_b32_e32 v152, v153
	v_pk_fma_f32 v[2:3], v[2:3], v[152:153], v[196:197] op_sel_hi:[1,0,1]
	v_pk_fma_f32 v[4:5], v[4:5], v[152:153], v[194:195] op_sel_hi:[1,0,1]
	v_pk_fma_f32 v[152:153], v[74:75], v[84:85], v[166:167] op_sel_hi:[1,0,1]
	v_pk_fma_f32 v[162:163], v[72:73], v[84:85], v[162:163] op_sel_hi:[1,0,1]
	v_pk_fma_f32 v[166:167], v[74:75], v[88:89], v[168:169] op_sel_hi:[1,0,1]
	v_pk_fma_f32 v[164:165], v[72:73], v[88:89], v[164:165] op_sel_hi:[1,0,1]
	v_pk_fma_f32 v[168:169], v[72:73], v[94:95], v[170:171] op_sel_hi:[1,0,1]
	v_pk_fma_f32 v[170:171], v[72:73], v[100:101], v[172:173] op_sel_hi:[1,0,1]
	v_pk_fma_f32 v[172:173], v[72:73], v[108:109], v[174:175] op_sel_hi:[1,0,1]
	v_pk_fma_f32 v[174:175], v[72:73], v[116:117], v[176:177] op_sel_hi:[1,0,1]
	v_pk_fma_f32 v[176:177], v[72:73], v[126:127], v[178:179] op_sel_hi:[1,0,1]
	v_pk_fma_f32 v[178:179], v[72:73], v[146:147], v[180:181] op_sel_hi:[1,0,1]
	s_waitcnt lgkmcnt(2)
	v_pk_fma_f32 v[72:73], v[72:73], v[154:155], v[2:3] op_sel_hi:[1,0,1]
	v_mov_b32_e32 v2, v85
	v_pk_fma_f32 v[84:85], v[78:79], v[2:3], v[152:153] op_sel_hi:[1,0,1]
	v_pk_fma_f32 v[152:153], v[76:77], v[2:3], v[162:163] op_sel_hi:[1,0,1]
	v_add_u32_e32 v2, 0x180, v112
	v_pk_fma_f32 v[114:115], v[74:75], v[116:117], v[114:115] op_sel_hi:[1,0,1]
	v_mov_b32_e32 v88, v89
	v_mad_i64_i32 v[2:3], s[10:11], v2, s72, v[64:65]
	v_mov_b32_e32 v116, v117
	v_add_u32_e32 v113, 0x1c0, v112
	v_pk_fma_f32 v[92:93], v[74:75], v[94:95], v[92:93] op_sel_hi:[1,0,1]
	v_pk_fma_f32 v[98:99], v[74:75], v[100:101], v[98:99] op_sel_hi:[1,0,1]
	v_pk_fma_f32 v[104:105], v[74:75], v[108:109], v[104:105] op_sel_hi:[1,0,1]
	v_pk_fma_f32 v[124:125], v[74:75], v[126:127], v[124:125] op_sel_hi:[1,0,1]
	v_pk_fma_f32 v[144:145], v[74:75], v[146:147], v[144:145] op_sel_hi:[1,0,1]
	v_pk_fma_f32 v[74:75], v[74:75], v[154:155], v[4:5] op_sel_hi:[1,0,1]
	v_mov_b64_e32 v[2:3], v[224:225]
	v_mov_b64_e32 v[4:5], v[226:227]
	v_pk_fma_f32 v[162:163], v[78:79], v[88:89], v[166:167] op_sel_hi:[1,0,1]
	v_pk_fma_f32 v[88:89], v[76:77], v[88:89], v[164:165] op_sel_hi:[1,0,1]
	v_pk_fma_f32 v[164:165], v[78:79], v[116:117], v[114:115] op_sel_hi:[1,0,1]
	v_mad_i64_i32 v[114:115], s[10:11], v113, s72, v[64:65]
	v_pk_fma_f32 v[166:167], v[76:77], v[116:117], v[174:175] op_sel_hi:[1,0,1]
	v_mov_b64_e32 v[114:115], v[228:229]
	v_mov_b64_e32 v[116:117], v[230:231]
	v_mov_b32_e32 v94, v95
	v_mov_b32_e32 v100, v101
	v_mov_b32_e32 v108, v109
	v_mov_b32_e32 v126, v127
	v_mov_b32_e32 v146, v147
	v_mov_b32_e32 v154, v155
	v_pk_fma_f32 v[92:93], v[78:79], v[94:95], v[92:93] op_sel_hi:[1,0,1]
	v_pk_fma_f32 v[94:95], v[76:77], v[94:95], v[168:169] op_sel_hi:[1,0,1]
	v_pk_fma_f32 v[98:99], v[78:79], v[100:101], v[98:99] op_sel_hi:[1,0,1]
	v_pk_fma_f32 v[100:101], v[76:77], v[100:101], v[170:171] op_sel_hi:[1,0,1]
	v_pk_fma_f32 v[104:105], v[78:79], v[108:109], v[104:105] op_sel_hi:[1,0,1]
	v_pk_fma_f32 v[108:109], v[76:77], v[108:109], v[172:173] op_sel_hi:[1,0,1]
	v_pk_fma_f32 v[124:125], v[78:79], v[126:127], v[124:125] op_sel_hi:[1,0,1]
	v_pk_fma_f32 v[126:127], v[76:77], v[126:127], v[176:177] op_sel_hi:[1,0,1]
	v_pk_fma_f32 v[144:145], v[78:79], v[146:147], v[144:145] op_sel_hi:[1,0,1]
	v_pk_fma_f32 v[146:147], v[76:77], v[146:147], v[178:179] op_sel_hi:[1,0,1]
	v_pk_fma_f32 v[72:73], v[76:77], v[154:155], v[72:73] op_sel_hi:[1,0,1]
	v_pk_fma_f32 v[74:75], v[78:79], v[154:155], v[74:75] op_sel_hi:[1,0,1]
	v_pk_fma_f32 v[78:79], v[6:7], v[86:87], v[152:153] op_sel_hi:[1,0,1]
	v_pk_fma_f32 v[88:89], v[6:7], v[90:91], v[88:89] op_sel_hi:[1,0,1]
	v_pk_fma_f32 v[94:95], v[6:7], v[96:97], v[94:95] op_sel_hi:[1,0,1]
	v_pk_fma_f32 v[100:101], v[6:7], v[102:103], v[100:101] op_sel_hi:[1,0,1]
	v_pk_fma_f32 v[108:109], v[6:7], v[110:111], v[108:109] op_sel_hi:[1,0,1]
	v_pk_fma_f32 v[154:155], v[6:7], v[120:121], v[166:167] op_sel_hi:[1,0,1]
	v_pk_fma_f32 v[126:127], v[6:7], v[140:141], v[126:127] op_sel_hi:[1,0,1]
	v_pk_fma_f32 v[146:147], v[6:7], v[148:149], v[146:147] op_sel_hi:[1,0,1]
	s_waitcnt lgkmcnt(1)
	v_pk_fma_f32 v[72:73], v[6:7], v[156:157], v[72:73] op_sel_hi:[1,0,1]
	v_add_u32_e32 v6, 0x200, v112
	v_mad_i64_i32 v[6:7], s[10:11], v6, s72, v[64:65]
	v_pk_fma_f32 v[76:77], v[8:9], v[86:87], v[84:85] op_sel_hi:[1,0,1]
	v_pk_fma_f32 v[84:85], v[8:9], v[90:91], v[162:163] op_sel_hi:[1,0,1]
	v_pk_fma_f32 v[92:93], v[8:9], v[96:97], v[92:93] op_sel_hi:[1,0,1]
	v_pk_fma_f32 v[98:99], v[8:9], v[102:103], v[98:99] op_sel_hi:[1,0,1]
	v_pk_fma_f32 v[104:105], v[8:9], v[110:111], v[104:105] op_sel_hi:[1,0,1]
	v_pk_fma_f32 v[152:153], v[8:9], v[120:121], v[164:165] op_sel_hi:[1,0,1]
	v_pk_fma_f32 v[124:125], v[8:9], v[140:141], v[124:125] op_sel_hi:[1,0,1]
	v_pk_fma_f32 v[144:145], v[8:9], v[148:149], v[144:145] op_sel_hi:[1,0,1]
	v_pk_fma_f32 v[74:75], v[8:9], v[156:157], v[74:75] op_sel_hi:[1,0,1]
	v_mov_b64_e32 v[6:7], v[236:237]
	v_mov_b64_e32 v[8:9], v[238:239]
	v_mov_b32_e32 v86, v87
	v_pk_fma_f32 v[76:77], v[82:83], v[86:87], v[76:77] op_sel_hi:[1,0,1]
	v_pk_fma_f32 v[78:79], v[80:81], v[86:87], v[78:79] op_sel_hi:[1,0,1]
	v_mov_b32_e32 v86, v91
	v_pk_fma_f32 v[84:85], v[82:83], v[86:87], v[84:85] op_sel_hi:[1,0,1]
	v_pk_fma_f32 v[86:87], v[80:81], v[86:87], v[88:89] op_sel_hi:[1,0,1]
	v_mov_b32_e32 v88, v97
	v_pk_fma_f32 v[90:91], v[82:83], v[88:89], v[92:93] op_sel_hi:[1,0,1]
	v_mov_b32_e32 v92, v103
	v_mov_b32_e32 v96, v111
	v_pk_fma_f32 v[88:89], v[80:81], v[88:89], v[94:95] op_sel_hi:[1,0,1]
	v_pk_fma_f32 v[94:95], v[82:83], v[92:93], v[98:99] op_sel_hi:[1,0,1]
	v_pk_fma_f32 v[98:99], v[82:83], v[96:97], v[104:105] op_sel_hi:[1,0,1]
	v_mov_b32_e32 v104, v141
	v_pk_fma_f32 v[92:93], v[80:81], v[92:93], v[100:101] op_sel_hi:[1,0,1]
	v_pk_fma_f32 v[96:97], v[80:81], v[96:97], v[108:109] op_sel_hi:[1,0,1]
	v_mov_b32_e32 v100, v121
	v_pk_fma_f32 v[108:109], v[82:83], v[104:105], v[124:125] op_sel_hi:[1,0,1]
	v_mov_b32_e32 v110, v149
	v_mov_b32_e32 v124, v157
	v_pk_fma_f32 v[102:103], v[82:83], v[100:101], v[152:153] op_sel_hi:[1,0,1]
	v_pk_fma_f32 v[100:101], v[80:81], v[100:101], v[154:155] op_sel_hi:[1,0,1]
	v_pk_fma_f32 v[104:105], v[80:81], v[104:105], v[126:127] op_sel_hi:[1,0,1]
	v_pk_fma_f32 v[120:121], v[82:83], v[110:111], v[144:145] op_sel_hi:[1,0,1]
	v_pk_fma_f32 v[110:111], v[80:81], v[110:111], v[146:147] op_sel_hi:[1,0,1]
	v_pk_fma_f32 v[72:73], v[80:81], v[124:125], v[72:73] op_sel_hi:[1,0,1]
	v_add_u32_e32 v80, 0x240, v112
	v_pk_fma_f32 v[74:75], v[82:83], v[124:125], v[74:75] op_sel_hi:[1,0,1]
	v_mad_i64_i32 v[80:81], s[10:11], v80, s72, v[64:65]
	v_pk_fma_f32 v[76:77], v[4:5], v[66:67], v[76:77] op_sel_hi:[1,0,1]
	v_pk_fma_f32 v[78:79], v[2:3], v[66:67], v[78:79] op_sel_hi:[1,0,1]
	v_mov_b32_e32 v66, v67
	v_pk_fma_f32 v[82:83], v[4:5], v[68:69], v[84:85] op_sel_hi:[1,0,1]
	v_pk_fma_f32 v[84:85], v[2:3], v[68:69], v[86:87] op_sel_hi:[1,0,1]
	v_pk_fma_f32 v[86:87], v[4:5], v[70:71], v[90:91] op_sel_hi:[1,0,1]
	v_pk_fma_f32 v[88:89], v[2:3], v[70:71], v[88:89] op_sel_hi:[1,0,1]
	v_pk_fma_f32 v[90:91], v[4:5], v[106:107], v[94:95] op_sel_hi:[1,0,1]
	v_pk_fma_f32 v[92:93], v[2:3], v[106:107], v[92:93] op_sel_hi:[1,0,1]
	v_pk_fma_f32 v[124:125], v[4:5], v[118:119], v[98:99] op_sel_hi:[1,0,1]
	v_pk_fma_f32 v[96:97], v[2:3], v[118:119], v[96:97] op_sel_hi:[1,0,1]
	v_pk_fma_f32 v[126:127], v[4:5], v[122:123], v[102:103] op_sel_hi:[1,0,1]
	v_pk_fma_f32 v[140:141], v[2:3], v[122:123], v[100:101] op_sel_hi:[1,0,1]
	v_pk_fma_f32 v[144:145], v[4:5], v[142:143], v[108:109] op_sel_hi:[1,0,1]
	v_pk_fma_f32 v[146:147], v[2:3], v[142:143], v[104:105] op_sel_hi:[1,0,1]
	v_pk_fma_f32 v[120:121], v[4:5], v[150:151], v[120:121] op_sel_hi:[1,0,1]
	v_pk_fma_f32 v[148:149], v[2:3], v[150:151], v[110:111] op_sel_hi:[1,0,1]
	s_waitcnt lgkmcnt(0)
	v_pk_fma_f32 v[152:153], v[4:5], v[158:159], v[74:75] op_sel_hi:[1,0,1]
	v_pk_fma_f32 v[154:155], v[2:3], v[158:159], v[72:73] op_sel_hi:[1,0,1]
	v_mov_b64_e32 v[2:3], v[240:241]
	v_mov_b64_e32 v[4:5], v[242:243]
	v_pk_fma_f32 v[104:105], v[116:117], v[66:67], v[76:77] op_sel_hi:[1,0,1]
	v_pk_fma_f32 v[102:103], v[114:115], v[66:67], v[78:79] op_sel_hi:[1,0,1]
	v_mov_b32_e32 v66, v69
	v_pk_fma_f32 v[110:111], v[116:117], v[66:67], v[82:83] op_sel_hi:[1,0,1]
	v_pk_fma_f32 v[108:109], v[114:115], v[66:67], v[84:85] op_sel_hi:[1,0,1]
	v_mov_b32_e32 v66, v71
	v_pk_fma_f32 v[100:101], v[116:117], v[66:67], v[86:87] op_sel_hi:[1,0,1]
	v_pk_fma_f32 v[98:99], v[114:115], v[66:67], v[88:89] op_sel_hi:[1,0,1]
	v_mov_b32_e32 v66, v107
	v_pk_fma_f32 v[94:95], v[116:117], v[66:67], v[90:91] op_sel_hi:[1,0,1]
	v_pk_fma_f32 v[92:93], v[114:115], v[66:67], v[92:93] op_sel_hi:[1,0,1]
	v_mov_b32_e32 v66, v119
	v_pk_fma_f32 v[88:89], v[116:117], v[66:67], v[124:125] op_sel_hi:[1,0,1]
	v_pk_fma_f32 v[90:91], v[114:115], v[66:67], v[96:97] op_sel_hi:[1,0,1]
	v_mov_b32_e32 v66, v123
	ds_read2st64_b32 v[72:73], v12 offset0:8 offset1:9
	v_pk_fma_f32 v[86:87], v[116:117], v[66:67], v[126:127] op_sel_hi:[1,0,1]
	v_pk_fma_f32 v[84:85], v[114:115], v[66:67], v[140:141] op_sel_hi:[1,0,1]
	v_mov_b32_e32 v66, v143
	v_pk_fma_f32 v[82:83], v[116:117], v[66:67], v[144:145] op_sel_hi:[1,0,1]
	v_pk_fma_f32 v[80:81], v[114:115], v[66:67], v[146:147] op_sel_hi:[1,0,1]
	v_mov_b32_e32 v66, v151
	v_pk_fma_f32 v[78:79], v[116:117], v[66:67], v[120:121] op_sel_hi:[1,0,1]
	v_pk_fma_f32 v[74:75], v[114:115], v[66:67], v[148:149] op_sel_hi:[1,0,1]
	v_mov_b32_e32 v66, v159
	v_pk_fma_f32 v[70:71], v[116:117], v[66:67], v[152:153] op_sel_hi:[1,0,1]
	v_pk_fma_f32 v[76:77], v[114:115], v[66:67], v[154:155] op_sel_hi:[1,0,1]
	ds_read2st64_b32 v[66:67], v12 offset0:10 offset1:11
	ds_read2st64_b32 v[68:69], v12 offset0:12 offset1:13
	ds_read2st64_b32 v[96:97], v12 offset0:14 offset1:15
	ds_read2st64_b32 v[124:125], v12 offset0:24 offset1:25
	s_waitcnt lgkmcnt(4)
	v_pk_fma_f32 v[122:123], v[8:9], v[72:73], v[104:105] op_sel_hi:[1,0,1]
	v_pk_fma_f32 v[126:127], v[6:7], v[72:73], v[102:103] op_sel_hi:[1,0,1]
	ds_read2st64_b32 v[106:107], v12 offset0:26 offset1:27
	ds_read2st64_b32 v[104:105], v12 offset0:28 offset1:29
	ds_read2st64_b32 v[102:103], v12 offset0:30 offset1:31
	ds_read2st64_b32 v[140:141], v12 offset0:40 offset1:41
	v_add_u32_e32 v72, 0x280, v112
	s_waitcnt lgkmcnt(4)
	v_pk_fma_f32 v[142:143], v[6:7], v[124:125], v[108:109] op_sel_hi:[1,0,1]
	v_mad_i64_i32 v[108:109], s[10:11], v72, s72, v[64:65]
	v_mov_b64_e32 v[114:115], v[244:245]
	v_mov_b64_e32 v[116:117], v[246:247]
	ds_read2st64_b32 v[144:145], v12 offset0:42 offset1:43
	ds_read2st64_b32 v[146:147], v12 offset0:44 offset1:45
	ds_read2st64_b32 v[108:109], v12 offset0:46 offset1:47
	ds_read2st64_b32 v[148:149], v12 offset0:56 offset1:57
	s_waitcnt lgkmcnt(4)
	v_pk_fma_f32 v[150:151], v[6:7], v[140:141], v[98:99] op_sel_hi:[1,0,1]
	ds_read2st64_b32 v[152:153], v12 offset0:58 offset1:59
	ds_read2st64_b32 v[154:155], v12 offset0:60 offset1:61
	ds_read2st64_b32 v[98:99], v12 offset0:62 offset1:63
	ds_read2st64_b32 v[156:157], v12 offset0:72 offset1:73
	v_add_u32_e32 v72, 0x2c0, v112
	s_waitcnt lgkmcnt(4)
	v_pk_fma_f32 v[158:159], v[6:7], v[148:149], v[92:93] op_sel_hi:[1,0,1]
	ds_read2st64_b32 v[162:163], v12 offset0:74 offset1:75
	ds_read2st64_b32 v[164:165], v12 offset0:76 offset1:77
	ds_read2st64_b32 v[92:93], v12 offset0:78 offset1:79
	ds_read2st64_b32 v[168:169], v12 offset0:88 offset1:89
	s_waitcnt lgkmcnt(4)
	v_pk_fma_f32 v[166:167], v[8:9], v[156:157], v[88:89] op_sel_hi:[1,0,1]
	v_mad_i64_i32 v[88:89], s[10:11], v72, s72, v[64:65]
	v_mov_b64_e32 v[118:119], v[248:249]
	v_mov_b64_e32 v[120:121], v[250:251]
	ds_read2st64_b32 v[170:171], v12 offset0:90 offset1:91
	ds_read2st64_b32 v[172:173], v12 offset0:92 offset1:93
	ds_read2st64_b32 v[88:89], v12 offset0:94 offset1:95
	ds_read2st64_b32 v[174:175], v12 offset0:104 offset1:105
	s_waitcnt lgkmcnt(4)
	v_pk_fma_f32 v[176:177], v[6:7], v[168:169], v[84:85] op_sel_hi:[1,0,1]
	ds_read2st64_b32 v[178:179], v12 offset0:106 offset1:107
	ds_read2st64_b32 v[180:181], v12 offset0:108 offset1:109
	ds_read2st64_b32 v[84:85], v12 offset0:110 offset1:111
	ds_read2st64_b32 v[182:183], v12 offset0:120 offset1:121
	v_pk_fma_f32 v[110:111], v[8:9], v[124:125], v[110:111] op_sel_hi:[1,0,1]
	s_waitcnt lgkmcnt(4)
	v_pk_fma_f32 v[184:185], v[6:7], v[174:175], v[80:81] op_sel_hi:[1,0,1]
	ds_read2st64_b32 v[186:187], v12 offset0:122 offset1:123
	ds_read2st64_b32 v[188:189], v12 offset0:124 offset1:125
	ds_read2st64_b32 v[80:81], v12 offset0:126 offset1:127
	ds_read2st64_b32 v[192:193], v12 offset0:136 offset1:137
	v_pk_fma_f32 v[90:91], v[6:7], v[156:157], v[90:91] op_sel_hi:[1,0,1]
	s_waitcnt lgkmcnt(4)
	v_pk_fma_f32 v[190:191], v[8:9], v[182:183], v[78:79] op_sel_hi:[1,0,1]
	v_pk_fma_f32 v[74:75], v[6:7], v[182:183], v[74:75] op_sel_hi:[1,0,1]
	ds_read2st64_b32 v[194:195], v12 offset0:138 offset1:139
	ds_read2st64_b32 v[196:197], v12 offset0:140 offset1:141
	ds_read2st64_b32 v[78:79], v12 offset0:142 offset1:143
	s_waitcnt lgkmcnt(3)
	v_pk_fma_f32 v[76:77], v[6:7], v[192:193], v[76:77] op_sel_hi:[1,0,1]
	v_mov_b32_e32 v6, v73
	v_mov_b32_e32 v12, v125
	v_pk_fma_f32 v[100:101], v[8:9], v[140:141], v[100:101] op_sel_hi:[1,0,1]
	v_pk_fma_f32 v[94:95], v[8:9], v[148:149], v[94:95] op_sel_hi:[1,0,1]
	v_pk_fma_f32 v[198:199], v[8:9], v[192:193], v[70:71] op_sel_hi:[1,0,1]
	v_add_u32_e32 v70, 0x340, v112
	v_pk_fma_f32 v[86:87], v[8:9], v[168:169], v[86:87] op_sel_hi:[1,0,1]
	v_pk_fma_f32 v[82:83], v[8:9], v[174:175], v[82:83] op_sel_hi:[1,0,1]
	v_mad_i64_i32 v[70:71], s[10:11], v70, s72, v[64:65]
	s_waitcnt vmcnt(0)
	v_mov_b64_e32 v[70:71], v[200:201]
	v_mov_b64_e32 v[72:73], v[202:203]
	v_pk_fma_f32 v[122:123], v[4:5], v[6:7], v[122:123] op_sel_hi:[1,0,1]
	v_pk_fma_f32 v[126:127], v[2:3], v[6:7], v[126:127] op_sel_hi:[1,0,1]
	v_pk_fma_f32 v[110:111], v[4:5], v[12:13], v[110:111] op_sel_hi:[1,0,1]
	v_add_u32_e32 v6, 0x300, v112
	v_pk_fma_f32 v[124:125], v[2:3], v[12:13], v[142:143] op_sel_hi:[1,0,1]
	v_mov_b32_e32 v12, v141
	v_mad_i64_i32 v[6:7], s[10:11], v6, s72, v[64:65]
	v_pk_fma_f32 v[100:101], v[4:5], v[12:13], v[100:101] op_sel_hi:[1,0,1]
	v_pk_fma_f32 v[140:141], v[2:3], v[12:13], v[150:151] op_sel_hi:[1,0,1]
	v_mov_b32_e32 v12, v149
	v_mov_b64_e32 v[6:7], v[204:205]
	v_mov_b64_e32 v[8:9], v[206:207]
	v_pk_fma_f32 v[94:95], v[4:5], v[12:13], v[94:95] op_sel_hi:[1,0,1]
	v_pk_fma_f32 v[142:143], v[2:3], v[12:13], v[158:159] op_sel_hi:[1,0,1]
	v_mov_b32_e32 v12, v157
	v_pk_fma_f32 v[148:149], v[4:5], v[12:13], v[166:167] op_sel_hi:[1,0,1]
	v_pk_fma_f32 v[90:91], v[2:3], v[12:13], v[90:91] op_sel_hi:[1,0,1]
	v_mov_b32_e32 v12, v169
	v_pk_fma_f32 v[86:87], v[4:5], v[12:13], v[86:87] op_sel_hi:[1,0,1]
	v_pk_fma_f32 v[150:151], v[2:3], v[12:13], v[176:177] op_sel_hi:[1,0,1]
	v_mov_b32_e32 v12, v175
	v_pk_fma_f32 v[82:83], v[4:5], v[12:13], v[82:83] op_sel_hi:[1,0,1]
	v_pk_fma_f32 v[156:157], v[2:3], v[12:13], v[184:185] op_sel_hi:[1,0,1]
	v_mov_b32_e32 v12, v183
	v_pk_fma_f32 v[158:159], v[4:5], v[12:13], v[190:191] op_sel_hi:[1,0,1]
	v_pk_fma_f32 v[74:75], v[2:3], v[12:13], v[74:75] op_sel_hi:[1,0,1]
	v_mov_b32_e32 v12, v193
	v_pk_fma_f32 v[166:167], v[4:5], v[12:13], v[198:199] op_sel_hi:[1,0,1]
	v_pk_fma_f32 v[76:77], v[2:3], v[12:13], v[76:77] op_sel_hi:[1,0,1]
	v_mov_b32_e32 v12, v67
	v_add_u32_e32 v2, 0x380, v112
	v_mad_i64_i32 v[2:3], s[10:11], v2, s72, v[64:65]
	v_mov_b64_e32 v[2:3], v[208:209]
	v_mov_b64_e32 v[4:5], v[210:211]
	v_pk_fma_f32 v[122:123], v[116:117], v[66:67], v[122:123] op_sel_hi:[1,0,1]
	v_pk_fma_f32 v[126:127], v[114:115], v[66:67], v[126:127] op_sel_hi:[1,0,1]
	v_pk_fma_f32 v[110:111], v[116:117], v[106:107], v[110:111] op_sel_hi:[1,0,1]
	v_pk_fma_f32 v[124:125], v[114:115], v[106:107], v[124:125] op_sel_hi:[1,0,1]
	v_pk_fma_f32 v[140:141], v[114:115], v[144:145], v[140:141] op_sel_hi:[1,0,1]
	v_pk_fma_f32 v[142:143], v[114:115], v[152:153], v[142:143] op_sel_hi:[1,0,1]
	v_pk_fma_f32 v[90:91], v[114:115], v[162:163], v[90:91] op_sel_hi:[1,0,1]
	v_pk_fma_f32 v[150:151], v[114:115], v[170:171], v[150:151] op_sel_hi:[1,0,1]
	v_pk_fma_f32 v[156:157], v[114:115], v[178:179], v[156:157] op_sel_hi:[1,0,1]
	v_pk_fma_f32 v[74:75], v[114:115], v[186:187], v[74:75] op_sel_hi:[1,0,1]
	s_waitcnt lgkmcnt(2)
	v_pk_fma_f32 v[76:77], v[114:115], v[194:195], v[76:77] op_sel_hi:[1,0,1]
	v_pk_fma_f32 v[100:101], v[116:117], v[144:145], v[100:101] op_sel_hi:[1,0,1]
	v_pk_fma_f32 v[94:95], v[116:117], v[152:153], v[94:95] op_sel_hi:[1,0,1]
	v_pk_fma_f32 v[114:115], v[120:121], v[12:13], v[122:123] op_sel_hi:[1,0,1]
	v_pk_fma_f32 v[122:123], v[118:119], v[12:13], v[126:127] op_sel_hi:[1,0,1]
	v_mov_b32_e32 v12, v107
	v_pk_fma_f32 v[106:107], v[120:121], v[12:13], v[110:111] op_sel_hi:[1,0,1]
	v_pk_fma_f32 v[110:111], v[118:119], v[12:13], v[124:125] op_sel_hi:[1,0,1]
	v_mov_b32_e32 v12, v145
	v_pk_fma_f32 v[100:101], v[120:121], v[12:13], v[100:101] op_sel_hi:[1,0,1]
	v_pk_fma_f32 v[124:125], v[118:119], v[12:13], v[140:141] op_sel_hi:[1,0,1]
	v_mov_b32_e32 v12, v153
	v_pk_fma_f32 v[94:95], v[120:121], v[12:13], v[94:95] op_sel_hi:[1,0,1]
	v_pk_fma_f32 v[126:127], v[118:119], v[12:13], v[142:143] op_sel_hi:[1,0,1]
	v_add_u32_e32 v12, 0x3c0, v112
	v_mad_i64_i32 v[64:65], s[10:11], v12, s72, v[64:65]
	v_mov_b64_e32 v[64:65], v[212:213]
	v_mov_b64_e32 v[66:67], v[214:215]
	v_pk_fma_f32 v[148:149], v[116:117], v[162:163], v[148:149] op_sel_hi:[1,0,1]
	v_mov_b32_e32 v12, v163
	v_pk_fma_f32 v[86:87], v[116:117], v[170:171], v[86:87] op_sel_hi:[1,0,1]
	v_pk_fma_f32 v[112:113], v[120:121], v[12:13], v[148:149] op_sel_hi:[1,0,1]
	v_pk_fma_f32 v[90:91], v[118:119], v[12:13], v[90:91] op_sel_hi:[1,0,1]
	v_mov_b32_e32 v12, v171
	v_pk_fma_f32 v[82:83], v[116:117], v[178:179], v[82:83] op_sel_hi:[1,0,1]
	v_pk_fma_f32 v[86:87], v[120:121], v[12:13], v[86:87] op_sel_hi:[1,0,1]
	v_pk_fma_f32 v[140:141], v[118:119], v[12:13], v[150:151] op_sel_hi:[1,0,1]
	v_mov_b32_e32 v12, v179
	v_pk_fma_f32 v[158:159], v[116:117], v[186:187], v[158:159] op_sel_hi:[1,0,1]
	v_pk_fma_f32 v[82:83], v[120:121], v[12:13], v[82:83] op_sel_hi:[1,0,1]
	v_pk_fma_f32 v[142:143], v[118:119], v[12:13], v[156:157] op_sel_hi:[1,0,1]
	v_mov_b32_e32 v12, v187
	v_pk_fma_f32 v[116:117], v[116:117], v[194:195], v[166:167] op_sel_hi:[1,0,1]
	v_pk_fma_f32 v[144:145], v[120:121], v[12:13], v[158:159] op_sel_hi:[1,0,1]
	v_pk_fma_f32 v[74:75], v[118:119], v[12:13], v[74:75] op_sel_hi:[1,0,1]
	v_mov_b32_e32 v12, v195
	v_pk_fma_f32 v[116:117], v[120:121], v[12:13], v[116:117] op_sel_hi:[1,0,1]
	v_pk_fma_f32 v[76:77], v[118:119], v[12:13], v[76:77] op_sel_hi:[1,0,1]
	v_mov_b32_e32 v12, v69
	v_pk_fma_f32 v[114:115], v[8:9], v[68:69], v[114:115] op_sel_hi:[1,0,1]
	v_pk_fma_f32 v[118:119], v[6:7], v[68:69], v[122:123] op_sel_hi:[1,0,1]
	v_pk_fma_f32 v[106:107], v[8:9], v[104:105], v[106:107] op_sel_hi:[1,0,1]
	v_pk_fma_f32 v[110:111], v[6:7], v[104:105], v[110:111] op_sel_hi:[1,0,1]
	v_pk_fma_f32 v[120:121], v[6:7], v[146:147], v[124:125] op_sel_hi:[1,0,1]
	v_pk_fma_f32 v[122:123], v[6:7], v[154:155], v[126:127] op_sel_hi:[1,0,1]
	v_pk_fma_f32 v[90:91], v[6:7], v[164:165], v[90:91] op_sel_hi:[1,0,1]
	v_pk_fma_f32 v[124:125], v[6:7], v[172:173], v[140:141] op_sel_hi:[1,0,1]
	v_pk_fma_f32 v[126:127], v[6:7], v[180:181], v[142:143] op_sel_hi:[1,0,1]
	v_pk_fma_f32 v[74:75], v[6:7], v[188:189], v[74:75] op_sel_hi:[1,0,1]
	s_waitcnt lgkmcnt(1)
	v_pk_fma_f32 v[6:7], v[6:7], v[196:197], v[76:77] op_sel_hi:[1,0,1]
	v_pk_fma_f32 v[68:69], v[72:73], v[12:13], v[114:115] op_sel_hi:[1,0,1]
	v_pk_fma_f32 v[76:77], v[70:71], v[12:13], v[118:119] op_sel_hi:[1,0,1]
	v_mov_b32_e32 v12, v105
	v_pk_fma_f32 v[100:101], v[8:9], v[146:147], v[100:101] op_sel_hi:[1,0,1]
	v_pk_fma_f32 v[104:105], v[72:73], v[12:13], v[106:107] op_sel_hi:[1,0,1]
	v_pk_fma_f32 v[106:107], v[70:71], v[12:13], v[110:111] op_sel_hi:[1,0,1]
	v_mov_b32_e32 v12, v147
	v_pk_fma_f32 v[94:95], v[8:9], v[154:155], v[94:95] op_sel_hi:[1,0,1]
	v_pk_fma_f32 v[100:101], v[72:73], v[12:13], v[100:101] op_sel_hi:[1,0,1]
	v_pk_fma_f32 v[110:111], v[70:71], v[12:13], v[120:121] op_sel_hi:[1,0,1]
	v_mov_b32_e32 v12, v155
	v_pk_fma_f32 v[112:113], v[8:9], v[164:165], v[112:113] op_sel_hi:[1,0,1]
	v_pk_fma_f32 v[94:95], v[72:73], v[12:13], v[94:95] op_sel_hi:[1,0,1]
	v_pk_fma_f32 v[114:115], v[70:71], v[12:13], v[122:123] op_sel_hi:[1,0,1]
	v_mov_b32_e32 v12, v165
	v_pk_fma_f32 v[86:87], v[8:9], v[172:173], v[86:87] op_sel_hi:[1,0,1]
	v_pk_fma_f32 v[112:113], v[72:73], v[12:13], v[112:113] op_sel_hi:[1,0,1]
	v_pk_fma_f32 v[90:91], v[70:71], v[12:13], v[90:91] op_sel_hi:[1,0,1]
	v_mov_b32_e32 v12, v173
	v_pk_fma_f32 v[82:83], v[8:9], v[180:181], v[82:83] op_sel_hi:[1,0,1]
	v_pk_fma_f32 v[140:141], v[8:9], v[188:189], v[144:145] op_sel_hi:[1,0,1]
	v_pk_fma_f32 v[8:9], v[8:9], v[196:197], v[116:117] op_sel_hi:[1,0,1]
	v_pk_fma_f32 v[86:87], v[72:73], v[12:13], v[86:87] op_sel_hi:[1,0,1]
	v_pk_fma_f32 v[116:117], v[70:71], v[12:13], v[124:125] op_sel_hi:[1,0,1]
	v_mov_b32_e32 v12, v181
	v_pk_fma_f32 v[82:83], v[72:73], v[12:13], v[82:83] op_sel_hi:[1,0,1]
	v_pk_fma_f32 v[118:119], v[70:71], v[12:13], v[126:127] op_sel_hi:[1,0,1]
	v_mov_b32_e32 v12, v189
	v_pk_fma_f32 v[120:121], v[72:73], v[12:13], v[140:141] op_sel_hi:[1,0,1]
	v_pk_fma_f32 v[74:75], v[70:71], v[12:13], v[74:75] op_sel_hi:[1,0,1]
	v_mov_b32_e32 v12, v197
	v_pk_fma_f32 v[6:7], v[70:71], v[12:13], v[6:7] op_sel_hi:[1,0,1]
	v_pk_fma_f32 v[8:9], v[72:73], v[12:13], v[8:9] op_sel_hi:[1,0,1]
	v_pk_fma_f32 v[68:69], v[4:5], v[96:97], v[68:69] op_sel_hi:[1,0,1]
	v_pk_fma_f32 v[70:71], v[2:3], v[96:97], v[76:77] op_sel_hi:[1,0,1]
	v_pk_fma_f32 v[72:73], v[4:5], v[102:103], v[104:105] op_sel_hi:[1,0,1]
	v_pk_fma_f32 v[76:77], v[2:3], v[102:103], v[106:107] op_sel_hi:[1,0,1]
	v_pk_fma_f32 v[104:105], v[2:3], v[108:109], v[110:111] op_sel_hi:[1,0,1]
	v_pk_fma_f32 v[106:107], v[2:3], v[98:99], v[114:115] op_sel_hi:[1,0,1]
	v_pk_fma_f32 v[110:111], v[4:5], v[92:93], v[112:113] op_sel_hi:[1,0,1]
	v_pk_fma_f32 v[90:91], v[2:3], v[92:93], v[90:91] op_sel_hi:[1,0,1]
	v_pk_fma_f32 v[112:113], v[2:3], v[88:89], v[116:117] op_sel_hi:[1,0,1]
	v_pk_fma_f32 v[114:115], v[2:3], v[84:85], v[118:119] op_sel_hi:[1,0,1]
	v_pk_fma_f32 v[118:119], v[2:3], v[80:81], v[74:75] op_sel_hi:[1,0,1]
	s_waitcnt lgkmcnt(0)
	v_pk_fma_f32 v[2:3], v[2:3], v[78:79], v[6:7] op_sel_hi:[1,0,1]
	v_mov_b32_e32 v6, v97
	v_mov_b32_e32 v12, v103
	v_pk_fma_f32 v[100:101], v[4:5], v[108:109], v[100:101] op_sel_hi:[1,0,1]
	v_pk_fma_f32 v[94:95], v[4:5], v[98:99], v[94:95] op_sel_hi:[1,0,1]
	v_pk_fma_f32 v[86:87], v[4:5], v[88:89], v[86:87] op_sel_hi:[1,0,1]
	v_pk_fma_f32 v[82:83], v[4:5], v[84:85], v[82:83] op_sel_hi:[1,0,1]
	v_pk_fma_f32 v[116:117], v[4:5], v[80:81], v[120:121] op_sel_hi:[1,0,1]
	v_pk_fma_f32 v[4:5], v[4:5], v[78:79], v[8:9] op_sel_hi:[1,0,1]
	v_pk_fma_f32 v[8:9], v[66:67], v[6:7], v[68:69] op_sel_hi:[1,0,1]
	v_pk_fma_f32 v[6:7], v[64:65], v[6:7], v[70:71] op_sel_hi:[1,0,1]
	v_pk_fma_f32 v[70:71], v[66:67], v[12:13], v[72:73] op_sel_hi:[1,0,1]
	v_pk_fma_f32 v[72:73], v[64:65], v[12:13], v[76:77] op_sel_hi:[1,0,1]
	v_mov_b32_e32 v12, v109
	v_pk_fma_f32 v[96:97], v[66:67], v[12:13], v[100:101] op_sel_hi:[1,0,1]
	v_pk_fma_f32 v[100:101], v[64:65], v[12:13], v[104:105] op_sel_hi:[1,0,1]
	v_mov_b32_e32 v12, v99
	v_pk_fma_f32 v[94:95], v[66:67], v[12:13], v[94:95] op_sel_hi:[1,0,1]
	v_pk_fma_f32 v[98:99], v[64:65], v[12:13], v[106:107] op_sel_hi:[1,0,1]
	v_mov_b32_e32 v12, v93
	v_pk_fma_f32 v[102:103], v[66:67], v[12:13], v[110:111] op_sel_hi:[1,0,1]
	v_pk_fma_f32 v[104:105], v[64:65], v[12:13], v[90:91] op_sel_hi:[1,0,1]
	v_mov_b32_e32 v12, v89
	v_pk_fma_f32 v[108:109], v[66:67], v[12:13], v[86:87] op_sel_hi:[1,0,1]
	v_pk_fma_f32 v[106:107], v[64:65], v[12:13], v[112:113] op_sel_hi:[1,0,1]
	v_mov_b32_e32 v12, v85
	v_pk_fma_f32 v[120:121], v[66:67], v[12:13], v[82:83] op_sel_hi:[1,0,1]
	v_pk_fma_f32 v[110:111], v[64:65], v[12:13], v[114:115] op_sel_hi:[1,0,1]
	v_mov_b32_e32 v12, v81
	v_pk_fma_f32 v[74:75], v[66:67], v[12:13], v[116:117] op_sel_hi:[1,0,1]
	v_pk_fma_f32 v[80:81], v[64:65], v[12:13], v[118:119] op_sel_hi:[1,0,1]
	v_mov_b32_e32 v12, v79
	v_pk_fma_f32 v[68:69], v[64:65], v[12:13], v[2:3] op_sel_hi:[1,0,1]
	v_and_b32_e32 v3, 64, v137
	v_pk_fma_f32 v[66:67], v[66:67], v[12:13], v[4:5] op_sel_hi:[1,0,1]
	v_xor_b32_e32 v2, 8, v137
	v_add_u32_e32 v12, 64, v3
	v_cmp_lt_i32_e32 vcc, v2, v12
	v_xor_b32_e32 v4, 16, v137
	s_nop 0
	v_cndmask_b32_e32 v2, v137, v2, vcc
	v_lshlrev_b32_e32 v140, 2, v2
	ds_bpermute_b32 v78, v140, v100
	ds_bpermute_b32 v79, v140, v101
	ds_bpermute_b32 v82, v140, v96
	ds_bpermute_b32 v83, v140, v97
	ds_bpermute_b32 v112, v140, v108
	ds_bpermute_b32 v113, v140, v109
	ds_bpermute_b32 v114, v140, v110
	ds_bpermute_b32 v115, v140, v111
	v_cmp_lt_i32_e32 vcc, v4, v12
	s_waitcnt lgkmcnt(6)
	v_pk_add_f32 v[78:79], v[100:101], v[78:79]
	s_waitcnt lgkmcnt(4)
	v_pk_add_f32 v[86:87], v[96:97], v[82:83]
	v_cndmask_b32_e32 v4, v137, v4, vcc
	v_lshlrev_b32_e32 v141, 2, v4
	s_waitcnt lgkmcnt(2)
	v_pk_add_f32 v[108:109], v[108:109], v[112:113]
	s_waitcnt lgkmcnt(0)
	v_pk_add_f32 v[114:115], v[110:111], v[114:115]
	ds_bpermute_b32 v84, v141, v78
	ds_bpermute_b32 v85, v141, v79
	ds_bpermute_b32 v88, v141, v86
	ds_bpermute_b32 v89, v141, v87
	ds_bpermute_b32 v112, v141, v108
	ds_bpermute_b32 v113, v141, v109
	ds_bpermute_b32 v116, v141, v114
	ds_bpermute_b32 v117, v141, v115
	ds_bpermute_b32 v118, v140, v120
	ds_bpermute_b32 v119, v140, v121
	s_waitcnt lgkmcnt(8)
	v_pk_add_f32 v[78:79], v[78:79], v[84:85]
	s_waitcnt lgkmcnt(6)
	v_pk_add_f32 v[84:85], v[86:87], v[88:89]
	ds_bpermute_b32 v88, v140, v98
	ds_bpermute_b32 v89, v140, v99
	ds_bpermute_b32 v90, v140, v94
	ds_bpermute_b32 v91, v140, v95
	s_waitcnt lgkmcnt(8)
	v_pk_add_f32 v[108:109], v[108:109], v[112:113]
	s_waitcnt lgkmcnt(6)
	v_pk_add_f32 v[112:113], v[114:115], v[116:117]
	s_waitcnt lgkmcnt(4)
	v_pk_add_f32 v[116:117], v[120:121], v[118:119]
	ds_bpermute_b32 v120, v140, v80
	ds_bpermute_b32 v121, v140, v81
	ds_bpermute_b32 v122, v140, v74
	ds_bpermute_b32 v123, v140, v75
	ds_bpermute_b32 v2, v140, v6
	ds_bpermute_b32 v3, v140, v7
	ds_bpermute_b32 v64, v140, v72
	ds_bpermute_b32 v65, v140, v73
	s_waitcnt lgkmcnt(10)
	v_pk_add_f32 v[88:89], v[98:99], v[88:89]
	s_waitcnt lgkmcnt(8)
	v_pk_add_f32 v[94:95], v[94:95], v[90:91]
	s_waitcnt lgkmcnt(6)
	v_pk_add_f32 v[80:81], v[80:81], v[120:121]
	s_waitcnt lgkmcnt(4)
	v_pk_add_f32 v[122:123], v[74:75], v[122:123]
	ds_bpermute_b32 v92, v141, v88
	ds_bpermute_b32 v93, v141, v89
	ds_bpermute_b32 v96, v141, v94
	ds_bpermute_b32 v97, v141, v95
	ds_bpermute_b32 v98, v140, v104
	ds_bpermute_b32 v99, v140, v105
	ds_bpermute_b32 v120, v141, v80
	ds_bpermute_b32 v121, v141, v81
	ds_bpermute_b32 v124, v141, v122
	ds_bpermute_b32 v125, v141, v123
	s_waitcnt lgkmcnt(12)
	v_pk_add_f32 v[2:3], v[6:7], v[2:3]
	v_xor_b32_e32 v6, 32, v137
	v_cmp_lt_i32_e32 vcc, v6, v12
	s_waitcnt lgkmcnt(10)
	v_pk_add_f32 v[64:65], v[72:73], v[64:65]
	ds_bpermute_b32 v7, v140, v9
	v_cndmask_b32_e32 v6, v137, v6, vcc
	v_lshlrev_b32_e32 v12, 2, v6
	ds_bpermute_b32 v6, v140, v8
	ds_bpermute_b32 v72, v141, v64
	ds_bpermute_b32 v73, v141, v65
	ds_bpermute_b32 v76, v140, v70
	ds_bpermute_b32 v77, v140, v71
	s_waitcnt lgkmcnt(14)
	v_pk_add_f32 v[88:89], v[88:89], v[92:93]
	s_waitcnt lgkmcnt(12)
	v_pk_add_f32 v[92:93], v[94:95], v[96:97]
	s_waitcnt lgkmcnt(10)
	v_pk_add_f32 v[96:97], v[104:105], v[98:99]
	ds_bpermute_b32 v100, v140, v102
	ds_bpermute_b32 v101, v140, v103
	ds_bpermute_b32 v104, v140, v106
	ds_bpermute_b32 v105, v140, v107
	s_waitcnt lgkmcnt(12)
	v_pk_add_f32 v[74:75], v[80:81], v[120:121]
	ds_bpermute_b32 v126, v140, v68
	ds_bpermute_b32 v127, v140, v69
	s_waitcnt lgkmcnt(12)
	v_pk_add_f32 v[80:81], v[122:123], v[124:125]
	ds_bpermute_b32 v122, v140, v66
	ds_bpermute_b32 v123, v140, v67
	s_waitcnt lgkmcnt(12)
	v_pk_add_f32 v[6:7], v[8:9], v[6:7]
	s_waitcnt lgkmcnt(10)
	v_pk_add_f32 v[64:65], v[64:65], v[72:73]
	s_waitcnt lgkmcnt(8)
	v_pk_add_f32 v[72:73], v[70:71], v[76:77]
	s_waitcnt lgkmcnt(6)
	v_pk_add_f32 v[100:101], v[102:103], v[100:101]
	s_waitcnt lgkmcnt(4)
	v_pk_add_f32 v[104:105], v[106:107], v[104:105]
	s_waitcnt lgkmcnt(2)
	v_pk_add_f32 v[68:69], v[68:69], v[126:127]
	s_waitcnt lgkmcnt(0)
	v_pk_add_f32 v[122:123], v[66:67], v[122:123]
	ds_bpermute_b32 v4, v141, v2
	ds_bpermute_b32 v5, v141, v3
	ds_bpermute_b32 v8, v141, v6
	ds_bpermute_b32 v9, v141, v7
	ds_bpermute_b32 v76, v141, v72
	ds_bpermute_b32 v77, v141, v73
	ds_bpermute_b32 v98, v141, v96
	ds_bpermute_b32 v99, v141, v97
	ds_bpermute_b32 v102, v141, v100
	ds_bpermute_b32 v103, v141, v101
	ds_bpermute_b32 v106, v141, v104
	ds_bpermute_b32 v107, v141, v105
	ds_bpermute_b32 v118, v141, v116
	ds_bpermute_b32 v119, v141, v117
	ds_bpermute_b32 v124, v141, v68
	ds_bpermute_b32 v125, v141, v69
	ds_bpermute_b32 v126, v141, v122
	ds_bpermute_b32 v127, v141, v123
	s_waitcnt lgkmcnt(14)
	v_pk_add_f32 v[2:3], v[2:3], v[4:5]
	v_pk_add_f32 v[6:7], v[6:7], v[8:9]
	s_waitcnt lgkmcnt(12)
	v_pk_add_f32 v[72:73], v[72:73], v[76:77]
	s_waitcnt lgkmcnt(10)
	v_pk_add_f32 v[96:97], v[96:97], v[98:99]
	s_waitcnt lgkmcnt(8)
	v_pk_add_f32 v[100:101], v[100:101], v[102:103]
	s_waitcnt lgkmcnt(6)
	v_pk_add_f32 v[104:105], v[104:105], v[106:107]
	s_waitcnt lgkmcnt(4)
	v_pk_add_f32 v[116:117], v[116:117], v[118:119]
	s_waitcnt lgkmcnt(2)
	v_pk_add_f32 v[68:69], v[68:69], v[124:125]
	s_waitcnt lgkmcnt(0)
	v_pk_add_f32 v[124:125], v[122:123], v[126:127]
	ds_bpermute_b32 v4, v12, v2
	ds_bpermute_b32 v5, v12, v3
	ds_bpermute_b32 v8, v12, v6
	ds_bpermute_b32 v9, v12, v7
	ds_bpermute_b32 v70, v12, v64
	ds_bpermute_b32 v71, v12, v65
	ds_bpermute_b32 v76, v12, v72
	ds_bpermute_b32 v77, v12, v73
	ds_bpermute_b32 v82, v12, v78
	ds_bpermute_b32 v83, v12, v79
	ds_bpermute_b32 v86, v12, v84
	ds_bpermute_b32 v87, v12, v85
	ds_bpermute_b32 v90, v12, v88
	ds_bpermute_b32 v91, v12, v89
	ds_bpermute_b32 v94, v12, v92
	ds_bpermute_b32 v95, v12, v93
	ds_bpermute_b32 v98, v12, v96
	ds_bpermute_b32 v99, v12, v97
	ds_bpermute_b32 v102, v12, v100
	ds_bpermute_b32 v103, v12, v101
	ds_bpermute_b32 v106, v12, v104
	ds_bpermute_b32 v107, v12, v105
	ds_bpermute_b32 v110, v12, v108
	ds_bpermute_b32 v111, v12, v109
	ds_bpermute_b32 v114, v12, v112
	ds_bpermute_b32 v115, v12, v113
	ds_bpermute_b32 v118, v12, v116
	ds_bpermute_b32 v119, v12, v117
	ds_bpermute_b32 v120, v12, v74
	ds_bpermute_b32 v121, v12, v75
	ds_bpermute_b32 v66, v12, v80
	ds_bpermute_b32 v67, v12, v81
	ds_bpermute_b32 v122, v12, v68
	ds_bpermute_b32 v123, v12, v69
	ds_bpermute_b32 v126, v12, v124
	ds_bpermute_b32 v127, v12, v125
	v_and_b32_e32 v12, 63, v55
	v_cmp_gt_u32_e32 vcc, 8, v12
	s_and_saveexec_b64 s[10:11], vcc
	s_cbranch_execz .LBB0_47
	v_lshrrev_b32_e32 v140, 6, v55
	s_waitcnt lgkmcnt(14)
	v_pk_add_f32 v[4:5], v[2:3], v[4:5]
	v_lshlrev_b32_e32 v2, 4, v12
	v_mul_lo_u32 v3, v140, s73
	v_pk_add_f32 v[6:7], v[6:7], v[8:9]
	v_add3_u32 v2, 0, v2, v3
	s_waitcnt lgkmcnt(0)
	v_pk_add_f32 v[124:125], v[124:125], v[126:127]
	v_pk_add_f32 v[122:123], v[68:69], v[122:123]
	v_pk_add_f32 v[68:69], v[80:81], v[66:67]
	v_pk_add_f32 v[66:67], v[74:75], v[120:121]
	v_pk_add_f32 v[116:117], v[116:117], v[118:119]
	v_pk_add_f32 v[114:115], v[112:113], v[114:115]
	v_pk_add_f32 v[108:109], v[108:109], v[110:111]
	v_pk_add_f32 v[106:107], v[104:105], v[106:107]
	v_pk_add_f32 v[100:101], v[100:101], v[102:103]
	v_pk_add_f32 v[98:99], v[96:97], v[98:99]
	v_pk_add_f32 v[92:93], v[92:93], v[94:95]
	v_pk_add_f32 v[90:91], v[88:89], v[90:91]
	v_pk_add_f32 v[80:81], v[84:85], v[86:87]
	v_pk_add_f32 v[78:79], v[78:79], v[82:83]
	v_pk_add_f32 v[72:73], v[72:73], v[76:77]
	v_pk_add_f32 v[70:71], v[64:65], v[70:71]
	ds_write_b128 v2, v[4:7] offset:36864
	ds_write_b128 v2, v[70:73] offset:36992
	ds_write_b128 v2, v[78:81] offset:37120
	ds_write_b128 v2, v[90:93] offset:37248
	ds_write_b128 v2, v[98:101] offset:37376
	ds_write_b128 v2, v[106:109] offset:37504
	ds_write_b128 v2, v[114:117] offset:37632
	ds_write_b128 v2, v[66:69] offset:37760
	ds_write_b128 v2, v[122:125] offset:37888

.LBB0_432:
	v_readlane_b32 s8, v254, 2
	v_readlane_b32 s9, v254, 3
	v_mov_b32_e32 v13, v234
	s_andn2_b64 vcc, exec, s[8:9]
	v_cndmask_b32_e64 v0, 0, 1, s[8:9]
	v_cmp_ne_u32_e64 s[6:7], 1, v0
	v_readfirstlane_b32 s20, v13
	s_cbranch_vccnz .LBB0_448
	v_lshlrev_b32_e32 v0, 4, v13
	v_add_u32_e32 v1, 0x2000, v0
	v_ashrrev_i32_e32 v2, 31, v1
	v_lshrrev_b32_e32 v2, 22, v2
	v_add_u32_e32 v2, v1, v2
	v_ashrrev_i32_e32 v12, 10, v2
	v_mul_i32_i24_e32 v2, 0x400, v12
	v_sub_u32_e32 v1, v1, v2
	v_lshrrev_b32_e32 v2, 4, v1
	v_bitop3_b32 v1, v2, v1, 32 bitop3:0x6c
	v_ashrrev_i32_e32 v2, 31, v1
	v_lshrrev_b32_e32 v2, 26, v2
	v_add_u32_e32 v2, v1, v2
	v_lshlrev_b32_e32 v3, 3, v12
	v_ashrrev_i32_e32 v14, 6, v2
	v_and_b32_e32 v3, -16, v3
	s_mov_b64 s[8:9], 0x600000
	v_add_u32_e32 v3, v14, v3
	v_lshl_add_u64 v[128:129], v[160:161], 0, s[8:9]
	v_and_b32_e32 v4, 3, v14
	s_mov_b32 s8, 0x1fffe0
	v_lshrrev_b32_e32 v5, 2, v3
	v_lshlrev_b32_e32 v6, 1, v3
	v_and_b32_e32 v2, 0xc0, v2
	v_and_or_b32 v4, v3, s8, v4
	v_and_b32_e32 v5, 4, v5
	v_and_b32_e32 v6, 24, v6
	v_sub_u32_e32 v1, v1, v2
	v_mov_b32_e32 v2, 1
	v_or3_b32 v4, v4, v5, v6
	v_lshlrev_b32_e32 v5, 5, v12
	v_ashrrev_i16_sdwa v1, v2, sext(v1) dst_sel:DWORD dst_unused:UNUSED_PAD src0_sel:DWORD src1_sel:BYTE_0
	v_and_b32_e32 v5, 32, v5
	v_bfe_i32 v15, v1, 0, 16
	v_add_lshl_u32 v1, v5, v15, 1
	v_lshl_add_u32 v130, v4, 11, v1
	v_lshl_add_u32 v132, v3, 11, v1
	v_bfe_i32 v1, v13, 27, 1
	v_lshrrev_b32_e32 v1, 22, v1
	v_add_u32_e32 v1, v0, v1
	v_and_b32_e32 v1, 0xfffffc00, v1
	v_sub_u32_e32 v0, v0, v1
	v_lshrrev_b32_e32 v1, 4, v0
	v_ashrrev_i32_e32 v3, 31, v13
	v_bitop3_b32 v0, v1, v0, 32 bitop3:0x6c
	v_lshrrev_b32_e32 v3, 26, v3
	v_ashrrev_i32_e32 v1, 31, v0
	v_add_u32_e32 v3, v13, v3
	v_lshrrev_b32_e32 v1, 26, v1
	v_ashrrev_i32_e32 v17, 6, v3
	v_add_u32_e32 v1, v0, v1
	v_lshlrev_b32_e32 v3, 3, v17
	v_ashrrev_i32_e32 v16, 6, v1
	v_and_b32_e32 v3, -16, v3
	v_add_u32_e32 v3, v16, v3
	v_and_b32_e32 v4, 3, v16
	v_and_or_b32 v4, v3, s8, v4
	s_lshr_b32 s8, s95, 31
	s_ashr_i32 s9, s95, 8
	s_add_i32 s8, s9, s8
	s_mul_i32 s9, s8, 0xfffffb80
	s_add_i32 s9, s9, s2
	s_ashr_i32 s10, s9, 31
	s_lshr_b32 s10, s10, 29
	s_add_i32 s10, s9, s10
	s_ashr_i32 s21, s20, 6
	s_ashr_i32 s11, s10, 3
	s_and_b32 s10, s10, -8
	s_ashr_i32 s24, s20, 8
	s_lshl_b32 s22, s21, 10
	s_sub_i32 s9, s9, s10
	s_cmp_lt_i32 s9, 0
	s_movk_i32 s23, 0x91
	s_cselect_b32 s10, s23, 0x90
	s_mul_i32 s9, s10, s9
	s_add_i32 s9, s9, s11
	s_mul_hi_i32 s10, s9, 0x2aaaaaab
	s_lshr_b32 s11, s10, 31
	s_ashr_i32 s10, s10, 7
	s_add_i32 s10, s10, s11
	s_lshl_b32 s11, s10, 3
	v_and_b32_e32 v1, 0xc0, v1
	s_sub_i32 s12, 12, s11
	v_sub_u32_e32 v0, v0, v1
	s_min_i32 s12, s12, 8
	v_ashrrev_i16_sdwa v0, v2, sext(v0) dst_sel:DWORD dst_unused:UNUSED_PAD src0_sel:DWORD src1_sel:BYTE_0
	s_abs_i32 s13, s12
	s_waitcnt vmcnt(0)
	v_bfe_i32 v18, v0, 0, 16
	v_cvt_f32_u32_e32 v0, s13
	s_sub_i32 s15, 0, s13
	s_mulk_i32 s10, 0x300
	s_sub_i32 s9, s9, s10
	v_rcp_iflag_f32_e32 v0, v0
	s_abs_i32 s14, s9
	s_xor_b32 s10, s9, s12
	s_ashr_i32 s10, s10, 31
	v_mul_f32_e32 v0, 0x4f7ffffe, v0
	v_cvt_u32_f32_e32 v0, v0
	v_lshrrev_b32_e32 v5, 2, v3
	v_lshlrev_b32_e32 v6, 1, v3
	v_and_b32_e32 v5, 4, v5
	v_readfirstlane_b32 s16, v0
	s_mul_i32 s15, s15, s16
	s_mul_hi_u32 s15, s16, s15
	s_add_i32 s16, s16, s15
	s_mul_hi_u32 s15, s14, s16
	s_mul_i32 s16, s15, s13
	s_sub_i32 s14, s14, s16
	s_add_i32 s16, s15, 1
	s_sub_i32 s17, s14, s13
	s_cmp_ge_u32 s14, s13
	s_cselect_b32 s15, s16, s15
	s_cselect_b32 s14, s17, s14
	s_add_i32 s16, s15, 1
	s_cmp_ge_u32 s14, s13
	s_cselect_b32 s13, s16, s15
	s_xor_b32 s13, s13, s10
	s_sub_i32 s36, s13, s10
	s_mul_i32 s10, s36, s12
	v_and_b32_e32 v6, 24, v6
	s_sub_i32 s9, s9, s10
	v_or3_b32 v4, v4, v5, v6
	v_lshlrev_b32_e32 v5, 5, v17
	s_add_i32 s38, s9, s11
	v_and_b32_e32 v5, 32, v5
	s_ashr_i32 s39, s38, 31
	v_add_lshl_u32 v1, v5, v18, 1
	s_lshl_b64 s[10:11], s[38:39], 19
	s_ashr_i32 s37, s36, 31
	v_lshl_add_u32 v136, v3, 11, v1
	s_ashr_i32 s9, s8, 31
	v_lshl_add_u64 v[2:3], v[128:129], 0, s[10:11]
	s_lshl_b64 s[10:11], s[36:37], 19
	v_lshl_add_u32 v134, v4, 11, v1
	s_lshl_b64 s[8:9], s[8:9], 11
	v_lshl_add_u64 v[0:1], v[184:185], 0, s[10:11]
	v_lshl_add_u64 v[0:1], v[0:1], 0, s[8:9]
	s_add_i32 s33, s22, 0
	v_mov_b32_e32 v135, 0
	s_add_i32 m0, s33, 0x10000
	v_lshl_add_u64 v[4:5], v[0:1], 0, v[134:135]
	v_mov_b32_e32 v131, v135
	s_mov_b64 s[10:11], 0x40000
	global_load_lds_dwordx4 v[4:5], off
	v_lshl_add_u64 v[6:7], v[0:1], 0, v[130:131]
	s_add_i32 m0, s33, 0x12000
	v_lshl_add_u64 v[8:9], v[0:1], 0, s[10:11]
	global_load_lds_dwordx4 v[6:7], off
	s_add_i32 m0, s33, 0x14000
	v_lshl_add_u64 v[10:11], v[8:9], 0, v[134:135]
	global_load_lds_dwordx4 v[10:11], off
	v_lshl_add_u64 v[8:9], v[8:9], 0, v[130:131]
	s_add_i32 m0, s33, 0x16000
	v_lshl_add_u64 v[2:3], v[2:3], 0, s[8:9]
	v_mov_b32_e32 v137, v135
	global_load_lds_dwordx4 v[8:9], off
	v_lshl_add_u64 v[8:9], v[2:3], 0, v[136:137]
	s_mov_b32 m0, s33
	v_mov_b32_e32 v133, v135
	s_add_i32 s37, s33, 0x2000
	global_load_lds_dwordx4 v[8:9], off
	v_lshl_add_u64 v[10:11], v[2:3], 0, v[132:133]
	s_mov_b32 m0, s37
	v_lshl_add_u64 v[20:21], v[2:3], 0, s[10:11]
	s_add_i32 s39, s33, 0x4000
	global_load_lds_dwordx4 v[10:11], off
	v_lshl_add_u64 v[22:23], v[20:21], 0, v[136:137]
	s_mov_b32 m0, s39
	s_add_i32 s42, s33, 0x6000
	global_load_lds_dwordx4 v[22:23], off
	v_lshl_add_u64 v[20:21], v[20:21], 0, v[132:133]
	s_mov_b32 m0, s42
	s_load_dwordx2 s[8:9], s[0:1], 0x58
	global_load_lds_dwordx4 v[20:21], off
	s_cmp_eq_u32 s24, 1
	s_cselect_b64 s[12:13], -1, 0
	s_cmp_lg_u32 s24, 1
	s_mov_b32 s43, 0
	s_cbranch_scc1 .LBB0_435
	s_barrier

.LBB0_444:
	s_lshl_b32 s29, s38, 8
	v_mov_b32_e32 v150, v158
	v_mov_b32_e32 v155, v159
	s_add_i32 s29, s29, s46
	s_andn2_b64 vcc, exec, s[8:9]
	v_add_u32_e32 v152, s29, v150
	v_ashrrev_i32_e32 v153, 31, v152
	v_lshl_add_u64 v[150:151], v[152:153], 2, s[14:15]
	global_load_dword v154, v[150:151], off
	global_load_dword v226, v[150:151], off offset:64
	global_load_dword v227, v[150:151], off offset:128
	global_load_dword v228, v[150:151], off offset:192
	global_load_dword v229, v[150:151], off offset:512
	global_load_dword v230, v[150:151], off offset:576
	global_load_dword v231, v[150:151], off offset:640
	global_load_dword v232, v[150:151], off offset:704
	s_lshl_b32 s29, s36, 8
	s_or_b32 s29, s29, s47
	v_lshl_add_u32 v150, v155, 3, s29
	v_ashrrev_i32_e32 v151, 31, v150
	v_mad_i64_i32 v[156:157], s[40:41], v152, s53, v[162:163]
	v_add_u32_e32 v168, 16, v152
	v_lshlrev_b64 v[150:151], 1, v[150:151]
	v_ashrrev_i32_e32 v169, 31, v168
	v_lshl_add_u64 v[156:157], v[156:157], 0, v[150:151]
	v_lshl_add_u64 v[170:171], v[168:169], 2, s[14:15]
	s_waitcnt vmcnt(0)
	v_pk_add_f32 v[126:127], v[126:127], v[154:155] op_sel_hi:[1,0]
	v_pk_add_f32 v[124:125], v[124:125], v[154:155] op_sel_hi:[1,0]
	v_pk_add_f32 v[122:123], v[122:123], v[154:155] op_sel_hi:[1,0]
	v_pk_add_f32 v[120:121], v[120:121], v[154:155] op_sel_hi:[1,0]
	v_pk_add_f32 v[118:119], v[118:119], v[154:155] op_sel_hi:[1,0]
	v_pk_add_f32 v[116:117], v[116:117], v[154:155] op_sel_hi:[1,0]
	v_pk_add_f32 v[172:173], v[114:115], v[154:155] op_sel_hi:[1,0]
	v_pk_add_f32 v[154:155], v[112:113], v[154:155] op_sel_hi:[1,0]
	v_cvt_pk_bf16_f32 v112, v124, v125
	v_cvt_pk_bf16_f32 v113, v126, v127
	v_cvt_pk_bf16_f32 v114, v120, v121
	v_cvt_pk_bf16_f32 v115, v122, v123
	v_cvt_pk_bf16_f32 v116, v116, v117
	v_cvt_pk_bf16_f32 v117, v118, v119
	v_cvt_pk_bf16_f32 v118, v154, v155
	v_cvt_pk_bf16_f32 v119, v172, v173
	global_store_dwordx4 v[156:157], v[112:115], off
	global_store_dwordx4 v[156:157], v[116:119], off offset:256
	s_nop 0
	v_add_u32_e32 v114, 32, v152
	v_mad_i64_i32 v[116:117], s[40:41], v168, s53, v[162:163]
	v_ashrrev_i32_e32 v115, 31, v114
	v_lshl_add_u64 v[116:117], v[116:117], 0, v[150:151]
	v_lshl_add_u64 v[118:119], v[114:115], 2, s[14:15]
	v_mov_b32_e32 v112, v226
	v_pk_add_f32 v[110:111], v[110:111], v[112:113] op_sel_hi:[1,0]
	v_pk_add_f32 v[108:109], v[108:109], v[112:113] op_sel_hi:[1,0]
	v_pk_add_f32 v[106:107], v[106:107], v[112:113] op_sel_hi:[1,0]
	v_pk_add_f32 v[104:105], v[104:105], v[112:113] op_sel_hi:[1,0]
	v_pk_add_f32 v[102:103], v[102:103], v[112:113] op_sel_hi:[1,0]
	v_pk_add_f32 v[100:101], v[100:101], v[112:113] op_sel_hi:[1,0]
	v_pk_add_f32 v[120:121], v[98:99], v[112:113] op_sel_hi:[1,0]
	v_pk_add_f32 v[112:113], v[96:97], v[112:113] op_sel_hi:[1,0]
	v_cvt_pk_bf16_f32 v96, v108, v109
	v_cvt_pk_bf16_f32 v97, v110, v111
	v_cvt_pk_bf16_f32 v98, v104, v105
	v_cvt_pk_bf16_f32 v99, v106, v107
	v_cvt_pk_bf16_f32 v100, v100, v101
	v_cvt_pk_bf16_f32 v101, v102, v103
	v_cvt_pk_bf16_f32 v102, v112, v113
	v_cvt_pk_bf16_f32 v103, v120, v121
	global_store_dwordx4 v[116:117], v[96:99], off
	global_store_dwordx4 v[116:117], v[100:103], off offset:256
	s_nop 0
	v_add_u32_e32 v98, 48, v152
	v_mad_i64_i32 v[100:101], s[40:41], v114, s53, v[162:163]
	v_ashrrev_i32_e32 v99, 31, v98
	v_lshl_add_u64 v[100:101], v[100:101], 0, v[150:151]
	v_lshl_add_u64 v[102:103], v[98:99], 2, s[14:15]
	v_mov_b32_e32 v96, v227
	v_pk_add_f32 v[94:95], v[94:95], v[96:97] op_sel_hi:[1,0]
	v_pk_add_f32 v[92:93], v[92:93], v[96:97] op_sel_hi:[1,0]
	v_pk_add_f32 v[90:91], v[90:91], v[96:97] op_sel_hi:[1,0]
	v_pk_add_f32 v[88:89], v[88:89], v[96:97] op_sel_hi:[1,0]
	v_pk_add_f32 v[86:87], v[86:87], v[96:97] op_sel_hi:[1,0]
	v_pk_add_f32 v[84:85], v[84:85], v[96:97] op_sel_hi:[1,0]
	v_pk_add_f32 v[104:105], v[82:83], v[96:97] op_sel_hi:[1,0]
	v_pk_add_f32 v[96:97], v[80:81], v[96:97] op_sel_hi:[1,0]
	v_cvt_pk_bf16_f32 v80, v92, v93
	v_cvt_pk_bf16_f32 v81, v94, v95
	v_cvt_pk_bf16_f32 v82, v88, v89
	v_cvt_pk_bf16_f32 v83, v90, v91
	v_cvt_pk_bf16_f32 v84, v84, v85
	v_cvt_pk_bf16_f32 v85, v86, v87
	v_cvt_pk_bf16_f32 v86, v96, v97
	v_cvt_pk_bf16_f32 v87, v104, v105
	global_store_dwordx4 v[100:101], v[80:83], off
	global_store_dwordx4 v[100:101], v[84:87], off offset:256
	s_nop 0
	v_add_u32_e32 v82, 0x80, v152
	v_mad_i64_i32 v[84:85], s[40:41], v98, s53, v[162:163]
	v_ashrrev_i32_e32 v83, 31, v82
	v_lshl_add_u64 v[84:85], v[84:85], 0, v[150:151]
	v_lshl_add_u64 v[86:87], v[82:83], 2, s[14:15]
	v_mov_b32_e32 v80, v228
	v_pk_add_f32 v[78:79], v[78:79], v[80:81] op_sel_hi:[1,0]
	v_pk_add_f32 v[76:77], v[76:77], v[80:81] op_sel_hi:[1,0]
	v_pk_add_f32 v[74:75], v[74:75], v[80:81] op_sel_hi:[1,0]
	v_pk_add_f32 v[72:73], v[72:73], v[80:81] op_sel_hi:[1,0]
	v_pk_add_f32 v[70:71], v[70:71], v[80:81] op_sel_hi:[1,0]
	v_pk_add_f32 v[68:69], v[68:69], v[80:81] op_sel_hi:[1,0]
	v_pk_add_f32 v[88:89], v[66:67], v[80:81] op_sel_hi:[1,0]
	v_pk_add_f32 v[80:81], v[64:65], v[80:81] op_sel_hi:[1,0]
	v_cvt_pk_bf16_f32 v64, v76, v77
	v_cvt_pk_bf16_f32 v65, v78, v79
	v_cvt_pk_bf16_f32 v66, v72, v73
	v_cvt_pk_bf16_f32 v67, v74, v75
	v_cvt_pk_bf16_f32 v68, v68, v69
	v_cvt_pk_bf16_f32 v69, v70, v71
	v_cvt_pk_bf16_f32 v70, v80, v81
	v_cvt_pk_bf16_f32 v71, v88, v89
	global_store_dwordx4 v[84:85], v[64:67], off
	global_store_dwordx4 v[84:85], v[68:71], off offset:256
	s_nop 0
	v_add_u32_e32 v66, 0x90, v152
	v_mad_i64_i32 v[68:69], s[40:41], v82, s53, v[162:163]
	v_ashrrev_i32_e32 v67, 31, v66
	v_lshl_add_u64 v[68:69], v[68:69], 0, v[150:151]
	v_lshl_add_u64 v[70:71], v[66:67], 2, s[14:15]
	v_mov_b32_e32 v64, v229
	v_pk_add_f32 v[62:63], v[62:63], v[64:65] op_sel_hi:[1,0]
	v_pk_add_f32 v[60:61], v[60:61], v[64:65] op_sel_hi:[1,0]
	v_pk_add_f32 v[58:59], v[58:59], v[64:65] op_sel_hi:[1,0]
	v_pk_add_f32 v[56:57], v[56:57], v[64:65] op_sel_hi:[1,0]
	v_pk_add_f32 v[54:55], v[54:55], v[64:65] op_sel_hi:[1,0]
	v_pk_add_f32 v[52:53], v[52:53], v[64:65] op_sel_hi:[1,0]
	v_pk_add_f32 v[72:73], v[50:51], v[64:65] op_sel_hi:[1,0]
	v_pk_add_f32 v[64:65], v[48:49], v[64:65] op_sel_hi:[1,0]
	v_cvt_pk_bf16_f32 v48, v60, v61
	v_cvt_pk_bf16_f32 v49, v62, v63
	v_cvt_pk_bf16_f32 v50, v56, v57
	v_cvt_pk_bf16_f32 v51, v58, v59
	v_cvt_pk_bf16_f32 v52, v52, v53
	v_cvt_pk_bf16_f32 v53, v54, v55
	v_cvt_pk_bf16_f32 v54, v64, v65
	v_cvt_pk_bf16_f32 v55, v72, v73
	global_store_dwordx4 v[68:69], v[48:51], off
	global_store_dwordx4 v[68:69], v[52:55], off offset:256
	s_nop 0
	v_add_u32_e32 v50, 0xa0, v152
	v_mad_i64_i32 v[52:53], s[40:41], v66, s53, v[162:163]
	v_ashrrev_i32_e32 v51, 31, v50
	v_lshl_add_u64 v[52:53], v[52:53], 0, v[150:151]
	v_lshl_add_u64 v[54:55], v[50:51], 2, s[14:15]
	v_mov_b32_e32 v48, v230
	v_pk_add_f32 v[46:47], v[46:47], v[48:49] op_sel_hi:[1,0]
	v_pk_add_f32 v[44:45], v[44:45], v[48:49] op_sel_hi:[1,0]
	v_pk_add_f32 v[42:43], v[42:43], v[48:49] op_sel_hi:[1,0]
	v_pk_add_f32 v[40:41], v[40:41], v[48:49] op_sel_hi:[1,0]
	v_pk_add_f32 v[38:39], v[38:39], v[48:49] op_sel_hi:[1,0]
	v_pk_add_f32 v[36:37], v[36:37], v[48:49] op_sel_hi:[1,0]
	v_pk_add_f32 v[56:57], v[34:35], v[48:49] op_sel_hi:[1,0]
	v_pk_add_f32 v[48:49], v[32:33], v[48:49] op_sel_hi:[1,0]
	v_cvt_pk_bf16_f32 v32, v44, v45
	v_cvt_pk_bf16_f32 v33, v46, v47
	v_cvt_pk_bf16_f32 v34, v40, v41
	v_cvt_pk_bf16_f32 v35, v42, v43
	v_cvt_pk_bf16_f32 v36, v36, v37
	v_cvt_pk_bf16_f32 v37, v38, v39
	v_cvt_pk_bf16_f32 v38, v48, v49
	v_cvt_pk_bf16_f32 v39, v56, v57
	global_store_dwordx4 v[52:53], v[32:35], off
	global_store_dwordx4 v[52:53], v[36:39], off offset:256
	s_nop 0
	v_add_u32_e32 v34, 0xb0, v152
	v_mad_i64_i32 v[36:37], s[40:41], v50, s53, v[162:163]
	v_ashrrev_i32_e32 v35, 31, v34
	v_lshl_add_u64 v[36:37], v[36:37], 0, v[150:151]
	v_lshl_add_u64 v[38:39], v[34:35], 2, s[14:15]
	v_mov_b32_e32 v32, v231
	v_pk_add_f32 v[30:31], v[30:31], v[32:33] op_sel_hi:[1,0]
	v_pk_add_f32 v[28:29], v[28:29], v[32:33] op_sel_hi:[1,0]
	v_pk_add_f32 v[26:27], v[26:27], v[32:33] op_sel_hi:[1,0]
	v_pk_add_f32 v[24:25], v[24:25], v[32:33] op_sel_hi:[1,0]
	v_pk_add_f32 v[22:23], v[22:23], v[32:33] op_sel_hi:[1,0]
	v_pk_add_f32 v[20:21], v[20:21], v[32:33] op_sel_hi:[1,0]
	v_pk_add_f32 v[40:41], v[18:19], v[32:33] op_sel_hi:[1,0]
	v_pk_add_f32 v[32:33], v[16:17], v[32:33] op_sel_hi:[1,0]
	v_cvt_pk_bf16_f32 v16, v28, v29
	v_cvt_pk_bf16_f32 v17, v30, v31
	v_cvt_pk_bf16_f32 v18, v24, v25
	v_cvt_pk_bf16_f32 v19, v26, v27
	v_cvt_pk_bf16_f32 v20, v20, v21
	v_cvt_pk_bf16_f32 v21, v22, v23
	v_cvt_pk_bf16_f32 v22, v32, v33
	v_cvt_pk_bf16_f32 v23, v40, v41
	global_store_dwordx4 v[36:37], v[16:19], off
	global_store_dwordx4 v[36:37], v[20:23], off offset:256
	s_nop 0
	v_mad_i64_i32 v[18:19], s[8:9], v34, s53, v[162:163]
	v_lshl_add_u64 v[18:19], v[18:19], 0, v[150:151]
	s_mov_b64 s[8:9], -1
	v_mov_b32_e32 v16, v232
	v_pk_add_f32 v[14:15], v[14:15], v[16:17] op_sel_hi:[1,0]
	v_pk_add_f32 v[12:13], v[12:13], v[16:17] op_sel_hi:[1,0]
	v_pk_add_f32 v[10:11], v[10:11], v[16:17] op_sel_hi:[1,0]
	v_pk_add_f32 v[8:9], v[8:9], v[16:17] op_sel_hi:[1,0]
	v_pk_add_f32 v[6:7], v[6:7], v[16:17] op_sel_hi:[1,0]
	v_pk_add_f32 v[4:5], v[4:5], v[16:17] op_sel_hi:[1,0]
	v_pk_add_f32 v[20:21], v[2:3], v[16:17] op_sel_hi:[1,0]
	v_pk_add_f32 v[16:17], v[0:1], v[16:17] op_sel_hi:[1,0]
	v_cvt_pk_bf16_f32 v0, v12, v13
	v_cvt_pk_bf16_f32 v1, v14, v15
	v_cvt_pk_bf16_f32 v2, v8, v9
	v_cvt_pk_bf16_f32 v3, v10, v11
	v_cvt_pk_bf16_f32 v4, v4, v5
	v_cvt_pk_bf16_f32 v5, v6, v7
	v_cvt_pk_bf16_f32 v6, v16, v17
	v_cvt_pk_bf16_f32 v7, v20, v21
	global_store_dwordx4 v[18:19], v[0:3], off
	global_store_dwordx4 v[18:19], v[4:7], off offset:256
	s_cbranch_vccnz .LBB0_437
	s_andn2_b64 vcc, exec, s[12:13]
	s_cbranch_vccnz .LBB0_436
	s_barrier
	s_branch .LBB0_436

.LBB0_690:
	v_ashrrev_i32_e32 v1, 31, v12
	v_lshrrev_b32_e32 v1, 26, v1
	v_add_u32_e32 v1, v12, v1
	v_ashrrev_i32_e32 v13, 6, v1
	v_bfe_i32 v1, v12, 27, 1
	v_lshlrev_b32_e32 v0, 4, v12
	v_lshrrev_b32_e32 v1, 22, v1
	v_add_u32_e32 v1, v0, v1
	v_and_b32_e32 v1, 0xfffffc00, v1
	v_sub_u32_e32 v1, v0, v1
	v_lshrrev_b32_e32 v2, 4, v1
	v_bitop3_b32 v1, v2, v1, 32 bitop3:0x6c
	v_ashrrev_i32_e32 v3, 31, v1
	v_lshrrev_b32_e32 v3, 26, v3
	v_add_u32_e32 v3, v1, v3
	v_lshlrev_b32_e32 v2, 3, v13
	v_ashrrev_i32_e32 v14, 6, v3
	v_and_b32_e32 v3, 0xc0, v3
	v_and_b32_e32 v2, -16, v2
	v_sub_u32_e32 v1, v1, v3
	v_mov_b32_e32 v3, 1
	s_mov_b64 s[6:7], 0xc00000
	v_add_u32_e32 v2, v14, v2
	v_ashrrev_i16_sdwa v1, v3, sext(v1) dst_sel:DWORD dst_unused:UNUSED_PAD src0_sel:DWORD src1_sel:BYTE_0
	v_lshl_add_u64 v[164:165], v[160:161], 0, s[6:7]
	v_lshlrev_b32_e32 v4, 5, v13
	v_bfe_i32 v15, v1, 0, 16
	v_lshlrev_b32_e32 v1, 1, v2
	v_lshrrev_b32_e32 v5, 2, v2
	v_and_b32_e32 v6, 3, v14
	s_mov_b32 s6, 0x1fffe0
	v_and_b32_e32 v4, 32, v4
	v_and_b32_e32 v1, 24, v1
	v_and_b32_e32 v5, 4, v5
	v_and_or_b32 v6, v2, s6, v6
	v_or3_b32 v1, v6, v5, v1
	v_add_lshl_u32 v4, v4, v15, 1
	v_add_u32_e32 v0, 0x2000, v0
	v_lshl_add_u32 v168, v1, 11, v4
	v_ashrrev_i32_e32 v1, 31, v0
	v_lshrrev_b32_e32 v1, 22, v1
	v_add_u32_e32 v1, v0, v1
	v_ashrrev_i32_e32 v16, 10, v1
	v_mul_i32_i24_e32 v1, 0x400, v16
	v_sub_u32_e32 v0, v0, v1
	v_lshrrev_b32_e32 v1, 4, v0
	v_bitop3_b32 v0, v1, v0, 32 bitop3:0x6c
	v_lshl_add_u32 v166, v2, 11, v4
	v_ashrrev_i32_e32 v2, 31, v0
	v_lshrrev_b32_e32 v2, 26, v2
	v_add_u32_e32 v2, v0, v2
	v_lshlrev_b32_e32 v1, 3, v16
	v_ashrrev_i32_e32 v17, 6, v2
	v_and_b32_e32 v2, 0xc0, v2
	v_and_b32_e32 v1, -16, v1
	v_sub_u32_e32 v0, v0, v2
	v_add_u32_e32 v1, v17, v1
	v_ashrrev_i16_sdwa v0, v3, sext(v0) dst_sel:DWORD dst_unused:UNUSED_PAD src0_sel:DWORD src1_sel:BYTE_0
	v_lshlrev_b32_e32 v4, 5, v16
	s_waitcnt vmcnt(0)
	v_bfe_i32 v18, v0, 0, 16
	v_lshlrev_b32_e32 v0, 1, v1
	v_lshrrev_b32_e32 v2, 2, v1
	v_and_b32_e32 v3, 3, v17
	v_and_b32_e32 v4, 32, v4
	v_and_b32_e32 v0, 24, v0
	v_and_b32_e32 v2, 4, v2
	v_and_or_b32 v3, v1, s6, v3
	s_waitcnt lgkmcnt(0)
	s_ashr_i32 s9, s8, 31
	v_or3_b32 v0, v3, v2, v0
	v_add_lshl_u32 v2, v4, v18, 1
	s_lshl_b64 s[10:11], s[8:9], 19
	s_ashr_i32 s35, s34, 31
	v_lshl_add_u32 v170, v1, 11, v2
	v_lshl_add_u32 v172, v0, 11, v2
	s_ashr_i32 s6, s20, 6
	v_lshl_add_u64 v[2:3], v[184:185], 0, s[10:11]
	s_lshl_b64 s[10:11], s[34:35], 19
	s_lshl_b32 s38, s6, 10
	v_lshl_add_u64 v[0:1], v[164:165], 0, s[10:11]
	v_lshl_add_u64 v[0:1], v[0:1], 0, s[12:13]
	s_add_i32 s39, s38, 0
	v_mov_b32_e32 v169, 0
	s_add_i32 m0, s39, 0x10000
	v_lshl_add_u64 v[4:5], v[0:1], 0, v[168:169]
	v_mov_b32_e32 v173, v169
	s_mov_b64 s[10:11], 0x40000
	global_load_lds_dwordx4 v[4:5], off
	v_lshl_add_u64 v[6:7], v[0:1], 0, v[172:173]
	s_add_i32 m0, s39, 0x12000
	v_lshl_add_u64 v[8:9], v[0:1], 0, s[10:11]
	global_load_lds_dwordx4 v[6:7], off
	s_add_i32 m0, s39, 0x14000
	v_lshl_add_u64 v[10:11], v[8:9], 0, v[168:169]
	global_load_lds_dwordx4 v[10:11], off
	v_lshl_add_u64 v[8:9], v[8:9], 0, v[172:173]
	s_add_i32 m0, s39, 0x16000
	v_lshl_add_u64 v[2:3], v[2:3], 0, s[12:13]
	v_mov_b32_e32 v167, v169
	global_load_lds_dwordx4 v[8:9], off
	v_lshl_add_u64 v[8:9], v[2:3], 0, v[166:167]
	s_mov_b32 m0, s39
	v_mov_b32_e32 v171, v169
	s_add_i32 s40, s39, 0x2000
	global_load_lds_dwordx4 v[8:9], off
	v_lshl_add_u64 v[10:11], v[2:3], 0, v[170:171]
	s_mov_b32 m0, s40
	v_lshl_add_u64 v[20:21], v[2:3], 0, s[10:11]
	s_add_i32 s41, s39, 0x4000
	global_load_lds_dwordx4 v[10:11], off
	v_lshl_add_u64 v[22:23], v[20:21], 0, v[166:167]
	s_mov_b32 m0, s41
	s_add_i32 s42, s39, 0x6000
	global_load_lds_dwordx4 v[22:23], off
	v_lshl_add_u64 v[20:21], v[20:21], 0, v[170:171]
	s_mov_b32 m0, s42
	s_load_dwordx2 s[12:13], s[0:1], 0x58
	global_load_lds_dwordx4 v[20:21], off
	s_ashr_i32 s7, s20, 8
	s_cmp_eq_u32 s7, 1
	s_cselect_b64 s[14:15], -1, 0
	s_cmp_lg_u32 s7, 1
	s_mov_b32 s43, 0
	s_cbranch_scc1 .LBB0_692
	s_barrier

.LBB0_950:
	v_ashrrev_i32_e32 v1, 31, v12
	v_lshrrev_b32_e32 v1, 26, v1
	v_add_u32_e32 v1, v12, v1
	v_ashrrev_i32_e32 v13, 6, v1
	v_bfe_i32 v1, v12, 27, 1
	v_lshlrev_b32_e32 v0, 4, v12
	v_lshrrev_b32_e32 v1, 22, v1
	v_add_u32_e32 v1, v0, v1
	v_and_b32_e32 v1, 0xfffffc00, v1
	v_sub_u32_e32 v1, v0, v1
	v_lshrrev_b32_e32 v2, 4, v1
	v_bitop3_b32 v1, v2, v1, 32 bitop3:0x6c
	v_ashrrev_i32_e32 v3, 31, v1
	v_lshrrev_b32_e32 v3, 26, v3
	v_add_u32_e32 v3, v1, v3
	v_lshlrev_b32_e32 v2, 3, v13
	v_ashrrev_i32_e32 v14, 6, v3
	v_and_b32_e32 v3, 0xc0, v3
	v_and_b32_e32 v2, -16, v2
	v_sub_u32_e32 v1, v1, v3
	v_mov_b32_e32 v3, 1
	s_mov_b64 s[4:5], 0x1600000
	v_add_u32_e32 v2, v14, v2
	v_ashrrev_i16_sdwa v1, v3, sext(v1) dst_sel:DWORD dst_unused:UNUSED_PAD src0_sel:DWORD src1_sel:BYTE_0
	v_lshl_add_u64 v[188:189], v[160:161], 0, s[4:5]
	v_lshlrev_b32_e32 v4, 5, v13
	v_bfe_i32 v15, v1, 0, 16
	v_lshlrev_b32_e32 v1, 1, v2
	v_lshrrev_b32_e32 v5, 2, v2
	v_and_b32_e32 v6, 3, v14
	s_mov_b32 s5, 0x1fffe0
	v_and_b32_e32 v4, 32, v4
	v_and_b32_e32 v1, 24, v1
	v_and_b32_e32 v5, 4, v5
	v_and_or_b32 v6, v2, s5, v6
	v_or3_b32 v1, v6, v5, v1
	v_add_lshl_u32 v4, v4, v15, 1
	v_add_u32_e32 v0, 0x2000, v0
	v_lshl_add_u32 v192, v1, 11, v4
	v_ashrrev_i32_e32 v1, 31, v0
	v_lshrrev_b32_e32 v1, 22, v1
	v_add_u32_e32 v1, v0, v1
	v_ashrrev_i32_e32 v16, 10, v1
	v_mul_i32_i24_e32 v1, 0x400, v16
	v_sub_u32_e32 v0, v0, v1
	v_lshrrev_b32_e32 v1, 4, v0
	v_bitop3_b32 v0, v1, v0, 32 bitop3:0x6c
	v_lshl_add_u32 v190, v2, 11, v4
	v_ashrrev_i32_e32 v2, 31, v0
	v_lshrrev_b32_e32 v2, 26, v2
	v_add_u32_e32 v2, v0, v2
	v_lshlrev_b32_e32 v1, 3, v16
	v_ashrrev_i32_e32 v17, 6, v2
	v_and_b32_e32 v2, 0xc0, v2
	v_and_b32_e32 v1, -16, v1
	v_sub_u32_e32 v0, v0, v2
	v_add_u32_e32 v1, v17, v1
	v_ashrrev_i16_sdwa v0, v3, sext(v0) dst_sel:DWORD dst_unused:UNUSED_PAD src0_sel:DWORD src1_sel:BYTE_0
	v_lshlrev_b32_e32 v4, 5, v16
	s_waitcnt vmcnt(0)
	v_bfe_i32 v18, v0, 0, 16
	v_lshlrev_b32_e32 v0, 1, v1
	v_lshrrev_b32_e32 v2, 2, v1
	v_and_b32_e32 v3, 3, v17
	v_and_b32_e32 v4, 32, v4
	v_and_b32_e32 v0, 24, v0
	v_and_b32_e32 v2, 4, v2
	v_and_or_b32 v3, v1, s5, v3
	s_ashr_i32 s7, s6, 31
	v_or3_b32 v0, v3, v2, v0
	v_add_lshl_u32 v2, v4, v18, 1
	s_lshl_b64 s[12:13], s[6:7], 19
	s_ashr_i32 s67, s66, 31
	s_ashr_i32 s4, s10, 6
	v_lshl_add_u32 v194, v1, 11, v2
	v_lshl_add_u32 v196, v0, 11, v2
	v_lshl_add_u64 v[2:3], v[186:187], 0, s[12:13]
	s_lshl_b64 s[12:13], s[66:67], 19
	s_lshl_b32 s68, s4, 10
	v_lshl_add_u64 v[0:1], v[188:189], 0, s[12:13]
	v_mov_b32_e32 v199, 0
	v_lshl_add_u64 v[0:1], v[0:1], 0, s[8:9]
	s_add_i32 s69, s68, 0
	v_mov_b32_e32 v193, v199
	s_add_i32 m0, s69, 0x10000
	v_lshl_add_u64 v[4:5], v[0:1], 0, v[192:193]
	v_mov_b32_e32 v197, v199
	s_mov_b64 s[16:17], 0x40000
	global_load_lds_dwordx4 v[4:5], off
	v_lshl_add_u64 v[6:7], v[0:1], 0, v[196:197]
	s_add_i32 m0, s69, 0x12000
	v_lshl_add_u64 v[8:9], v[0:1], 0, s[16:17]
	global_load_lds_dwordx4 v[6:7], off
	s_add_i32 m0, s69, 0x14000
	v_lshl_add_u64 v[10:11], v[8:9], 0, v[192:193]
	global_load_lds_dwordx4 v[10:11], off
	v_lshl_add_u64 v[8:9], v[8:9], 0, v[196:197]
	s_add_i32 m0, s69, 0x16000
	v_lshl_add_u64 v[2:3], v[2:3], 0, s[8:9]
	v_mov_b32_e32 v191, v199
	global_load_lds_dwordx4 v[8:9], off
	v_lshl_add_u64 v[8:9], v[2:3], 0, v[190:191]
	s_mov_b32 m0, s69
	v_mov_b32_e32 v195, v199
	s_add_i32 s70, s69, 0x2000
	global_load_lds_dwordx4 v[8:9], off
	v_lshl_add_u64 v[10:11], v[2:3], 0, v[194:195]
	s_mov_b32 m0, s70
	v_lshl_add_u64 v[20:21], v[2:3], 0, s[16:17]
	s_add_i32 s71, s69, 0x4000
	global_load_lds_dwordx4 v[10:11], off
	v_lshl_add_u64 v[22:23], v[20:21], 0, v[190:191]
	s_mov_b32 m0, s71
	s_add_i32 s72, s69, 0x6000
	global_load_lds_dwordx4 v[22:23], off
	v_lshl_add_u64 v[20:21], v[20:21], 0, v[194:195]
	s_mov_b32 m0, s72
	s_ashr_i32 s5, s10, 8
	global_load_lds_dwordx4 v[20:21], off
	s_load_dwordx4 s[12:15], s[0:1], 0x0
	s_load_dwordx2 s[18:19], s[0:1], 0xd0
	s_load_dwordx2 s[20:21], s[0:1], 0x100
	s_cmp_eq_u32 s5, 1
	s_cselect_b64 s[22:23], -1, 0
	s_cmp_lg_u32 s5, 1
	s_mov_b32 s25, 0
	s_cbranch_scc1 .LBB0_952
	s_barrier
